# gate GEMM epilogues (P5, P13) rewritten by hand: x1/ple loads pipelined 8 groups ahead with counted vmcnt, n=0/n=1 tiles as one 16-byte access, packed-f32 sigmoid
# speedup vs baseline: 1.1376x; 1.0335x over previous
.LBB0_878:
	ds_read_b128 v[140:143], v149
	ds_read_b128 v[152:155], v149 offset:1024
	ds_read_b128 v[156:159], v149 offset:2048
	ds_read_b128 v[160:163], v149 offset:3072
	s_add_u32 s36, s22, 0xfffc0080
	s_addc_u32 s37, s23, -1
	s_cmp_eq_u32 s59, 12
	s_cselect_b32 s39, s11, s37
	s_cselect_b32 s38, s15, s36
	s_cselect_b32 s37, s49, s58
	s_cselect_b32 s36, s56, s57
	v_lshl_add_u64 v[144:145], s[22:23], 0, v[132:133]
	s_add_i32 m0, s21, 0xc000
	ds_read_b128 v[164:167], v150
	ds_read_b128 v[168:171], v150 offset:1024
	ds_read_b128 v[172:175], v150 offset:2048
	ds_read_b128 v[176:179], v150 offset:3072
	ds_read_b128 v[180:183], v150 offset:4096
	ds_read_b128 v[184:187], v150 offset:5120
	ds_read_b128 v[188:191], v150 offset:6144
	ds_read_b128 v[192:195], v150 offset:7168
	global_load_lds_dwordx4 v[144:145], off
	v_lshl_add_u64 v[144:145], s[22:23], 0, v[134:135]
	s_add_i32 m0, s21, 0xe000
	s_nop 0
	global_load_lds_dwordx4 v[144:145], off
	s_waitcnt lgkmcnt(8)
	s_barrier
	s_waitcnt lgkmcnt(0)
	s_setprio 1
	s_waitcnt lgkmcnt(0)
	v_mfma_f32_16x16x32_bf16 v[124:127], v[140:143], v[164:167], v[124:127]
	v_mfma_f32_16x16x32_bf16 v[120:123], v[156:159], v[164:167], v[120:123]
	v_mfma_f32_16x16x32_bf16 v[108:111], v[140:143], v[172:175], v[108:111]
	v_mfma_f32_16x16x32_bf16 v[104:107], v[156:159], v[172:175], v[104:107]
	v_mfma_f32_16x16x32_bf16 v[92:95], v[140:143], v[180:183], v[92:95]
	v_mfma_f32_16x16x32_bf16 v[88:91], v[156:159], v[180:183], v[88:91]
	v_mfma_f32_16x16x32_bf16 v[76:79], v[140:143], v[188:191], v[76:79]
	v_mfma_f32_16x16x32_bf16 v[72:75], v[156:159], v[188:191], v[72:75]
	v_mfma_f32_16x16x32_bf16 v[124:127], v[152:155], v[168:171], v[124:127]
	v_mfma_f32_16x16x32_bf16 v[120:123], v[160:163], v[168:171], v[120:123]
	v_mfma_f32_16x16x32_bf16 v[108:111], v[152:155], v[176:179], v[108:111]
	v_mfma_f32_16x16x32_bf16 v[104:107], v[160:163], v[176:179], v[104:107]
	v_mfma_f32_16x16x32_bf16 v[92:95], v[152:155], v[184:187], v[92:95]
	v_mfma_f32_16x16x32_bf16 v[88:91], v[160:163], v[184:187], v[88:91]
	v_mfma_f32_16x16x32_bf16 v[76:79], v[152:155], v[192:195], v[76:79]
	v_mfma_f32_16x16x32_bf16 v[72:75], v[160:163], v[192:195], v[72:75]
	s_setprio 0
	s_barrier
	s_add_i32 s60, s42, s25
	v_lshl_add_u64 v[144:145], s[36:37], 0, v[130:131]
	s_mov_b32 m0, s60
	ds_read_b128 v[200:203], v151
	ds_read_b128 v[204:207], v151 offset:1024
	ds_read_b128 v[208:211], v151 offset:2048
	ds_read_b128 v[212:215], v151 offset:3072
	global_load_lds_dwordx4 v[144:145], off
	v_lshl_add_u64 v[196:197], s[36:37], 0, v[128:129]
	s_add_i32 m0, s60, 0x2000
	s_nop 0
	global_load_lds_dwordx4 v[196:197], off
	s_barrier
	s_waitcnt lgkmcnt(0)
	s_setprio 1
	s_waitcnt lgkmcnt(0)
	v_mfma_f32_16x16x32_bf16 v[116:119], v[200:203], v[164:167], v[116:119]
	v_mfma_f32_16x16x32_bf16 v[112:115], v[208:211], v[164:167], v[112:115]
	v_mfma_f32_16x16x32_bf16 v[100:103], v[200:203], v[172:175], v[100:103]
	v_mfma_f32_16x16x32_bf16 v[96:99], v[208:211], v[172:175], v[96:99]
	v_mfma_f32_16x16x32_bf16 v[84:87], v[200:203], v[180:183], v[84:87]
	v_mfma_f32_16x16x32_bf16 v[80:83], v[208:211], v[180:183], v[80:83]
	v_mfma_f32_16x16x32_bf16 v[68:71], v[200:203], v[188:191], v[68:71]
	v_mfma_f32_16x16x32_bf16 v[64:67], v[208:211], v[188:191], v[64:67]
	v_mfma_f32_16x16x32_bf16 v[116:119], v[204:207], v[168:171], v[116:119]
	v_mfma_f32_16x16x32_bf16 v[112:115], v[212:215], v[168:171], v[112:115]
	v_mfma_f32_16x16x32_bf16 v[100:103], v[204:207], v[176:179], v[100:103]
	v_mfma_f32_16x16x32_bf16 v[96:99], v[212:215], v[176:179], v[96:99]
	v_mfma_f32_16x16x32_bf16 v[84:87], v[204:207], v[184:187], v[84:87]
	v_mfma_f32_16x16x32_bf16 v[80:83], v[212:215], v[184:187], v[80:83]
	v_mfma_f32_16x16x32_bf16 v[68:71], v[204:207], v[192:195], v[68:71]
	v_mfma_f32_16x16x32_bf16 v[64:67], v[212:215], v[192:195], v[64:67]
	s_setprio 0
	s_mov_b32 m0, s21
	v_lshl_add_u64 v[216:217], s[38:39], 0, v[130:131]
	s_barrier
	ds_read_b128 v[164:167], v150 offset:16384
	ds_read_b128 v[168:171], v150 offset:17408
	ds_read_b128 v[172:175], v150 offset:18432
	ds_read_b128 v[176:179], v150 offset:19456
	ds_read_b128 v[180:183], v150 offset:20480
	ds_read_b128 v[184:187], v150 offset:21504
	ds_read_b128 v[188:191], v150 offset:22528
	ds_read_b128 v[192:195], v150 offset:23552
	global_load_lds_dwordx4 v[216:217], off
	v_lshl_add_u64 v[218:219], s[38:39], 0, v[128:129]
	s_mov_b32 m0, s26
	s_nop 0
	global_load_lds_dwordx4 v[218:219], off
	s_barrier
	s_waitcnt lgkmcnt(0)
	s_setprio 1
	s_waitcnt lgkmcnt(0)
	v_mfma_f32_16x16x32_bf16 v[60:63], v[140:143], v[164:167], v[60:63]
	v_mfma_f32_16x16x32_bf16 v[56:59], v[156:159], v[164:167], v[56:59]
	v_mfma_f32_16x16x32_bf16 v[44:47], v[140:143], v[172:175], v[44:47]
	v_mfma_f32_16x16x32_bf16 v[40:43], v[156:159], v[172:175], v[40:43]
	v_mfma_f32_16x16x32_bf16 v[28:31], v[140:143], v[180:183], v[28:31]
	v_mfma_f32_16x16x32_bf16 v[24:27], v[156:159], v[180:183], v[24:27]
	v_mfma_f32_16x16x32_bf16 v[12:15], v[140:143], v[188:191], v[12:15]
	v_mfma_f32_16x16x32_bf16 v[8:11], v[156:159], v[188:191], v[8:11]
	v_mfma_f32_16x16x32_bf16 v[60:63], v[152:155], v[168:171], v[60:63]
	v_mfma_f32_16x16x32_bf16 v[56:59], v[160:163], v[168:171], v[56:59]
	v_mfma_f32_16x16x32_bf16 v[44:47], v[152:155], v[176:179], v[44:47]
	v_mfma_f32_16x16x32_bf16 v[40:43], v[160:163], v[176:179], v[40:43]
	v_mfma_f32_16x16x32_bf16 v[28:31], v[152:155], v[184:187], v[28:31]
	v_mfma_f32_16x16x32_bf16 v[24:27], v[160:163], v[184:187], v[24:27]
	v_mfma_f32_16x16x32_bf16 v[12:15], v[152:155], v[192:195], v[12:15]
	v_mfma_f32_16x16x32_bf16 v[8:11], v[160:163], v[192:195], v[8:11]
	s_setprio 0
	s_barrier
	s_add_u32 s60, s36, 0x40000
	s_addc_u32 s61, s37, 0
	s_add_i32 s62, s43, s25
	v_lshl_add_u64 v[140:141], s[60:61], 0, v[130:131]
	s_mov_b32 m0, s62
	s_nop 0
	global_load_lds_dwordx4 v[140:141], off
	v_lshl_add_u64 v[140:141], s[60:61], 0, v[128:129]
	s_add_i32 m0, s62, 0x2000
	s_nop 0
	global_load_lds_dwordx4 v[140:141], off
	s_waitcnt vmcnt(6)
	s_barrier
	s_setprio 1
	v_mfma_f32_16x16x32_bf16 v[52:55], v[200:203], v[164:167], v[52:55]
	v_mfma_f32_16x16x32_bf16 v[48:51], v[208:211], v[164:167], v[48:51]
	v_mfma_f32_16x16x32_bf16 v[36:39], v[200:203], v[172:175], v[36:39]
	v_mfma_f32_16x16x32_bf16 v[32:35], v[208:211], v[172:175], v[32:35]
	v_mfma_f32_16x16x32_bf16 v[20:23], v[200:203], v[180:183], v[20:23]
	v_mfma_f32_16x16x32_bf16 v[16:19], v[208:211], v[180:183], v[16:19]
	v_mfma_f32_16x16x32_bf16 v[4:7], v[200:203], v[188:191], v[4:7]
	v_mfma_f32_16x16x32_bf16 v[0:3], v[208:211], v[188:191], v[0:3]
	v_mfma_f32_16x16x32_bf16 v[52:55], v[204:207], v[168:171], v[52:55]
	v_mfma_f32_16x16x32_bf16 v[48:51], v[212:215], v[168:171], v[48:51]
	v_mfma_f32_16x16x32_bf16 v[36:39], v[204:207], v[176:179], v[36:39]
	v_mfma_f32_16x16x32_bf16 v[32:35], v[212:215], v[176:179], v[32:35]
	v_mfma_f32_16x16x32_bf16 v[20:23], v[204:207], v[184:187], v[20:23]
	v_mfma_f32_16x16x32_bf16 v[16:19], v[212:215], v[184:187], v[16:19]
	v_mfma_f32_16x16x32_bf16 v[4:7], v[204:207], v[192:195], v[4:7]
	v_mfma_f32_16x16x32_bf16 v[0:3], v[212:215], v[192:195], v[0:3]
	s_setprio 0
	s_add_i32 s60, 0, 0x18000
	v_add_u32_e32 v160, s60, v147
	s_barrier
	ds_read_b128 v[140:143], v160
	ds_read_b128 v[152:155], v160 offset:1024
	ds_read_b128 v[156:159], v160 offset:2048
	ds_read_b128 v[160:163], v160 offset:3072
	s_add_u32 s38, s38, 0x40000
	s_addc_u32 s39, s39, 0
	s_mov_b32 m0, s27
	v_lshl_add_u64 v[200:201], s[38:39], 0, v[130:131]
	ds_read_b128 v[164:167], v150 offset:32768
	ds_read_b128 v[168:171], v150 offset:33792
	ds_read_b128 v[172:175], v150 offset:34816
	ds_read_b128 v[176:179], v150 offset:35840
	ds_read_b128 v[180:183], v150 offset:36864
	ds_read_b128 v[184:187], v150 offset:37888
	ds_read_b128 v[188:191], v150 offset:38912
	ds_read_b128 v[192:195], v150 offset:39936
	global_load_lds_dwordx4 v[200:201], off
	v_lshl_add_u64 v[200:201], s[38:39], 0, v[128:129]
	s_mov_b32 m0, s28
	s_nop 0
	global_load_lds_dwordx4 v[200:201], off
	s_waitcnt lgkmcnt(8)
	s_barrier
	s_waitcnt lgkmcnt(0)
	s_setprio 1
	s_waitcnt lgkmcnt(0)
	v_mfma_f32_16x16x32_bf16 v[124:127], v[140:143], v[164:167], v[124:127]
	v_mfma_f32_16x16x32_bf16 v[120:123], v[156:159], v[164:167], v[120:123]
	v_mfma_f32_16x16x32_bf16 v[108:111], v[140:143], v[172:175], v[108:111]
	v_mfma_f32_16x16x32_bf16 v[104:107], v[156:159], v[172:175], v[104:107]
	v_mfma_f32_16x16x32_bf16 v[92:95], v[140:143], v[180:183], v[92:95]
	v_mfma_f32_16x16x32_bf16 v[88:91], v[156:159], v[180:183], v[88:91]
	v_mfma_f32_16x16x32_bf16 v[76:79], v[140:143], v[188:191], v[76:79]
	v_mfma_f32_16x16x32_bf16 v[72:75], v[156:159], v[188:191], v[72:75]
	v_mfma_f32_16x16x32_bf16 v[124:127], v[152:155], v[168:171], v[124:127]
	v_mfma_f32_16x16x32_bf16 v[120:123], v[160:163], v[168:171], v[120:123]
	v_mfma_f32_16x16x32_bf16 v[108:111], v[152:155], v[176:179], v[108:111]
	v_mfma_f32_16x16x32_bf16 v[104:107], v[160:163], v[176:179], v[104:107]
	v_mfma_f32_16x16x32_bf16 v[92:95], v[152:155], v[184:187], v[92:95]
	v_mfma_f32_16x16x32_bf16 v[88:91], v[160:163], v[184:187], v[88:91]
	v_mfma_f32_16x16x32_bf16 v[76:79], v[152:155], v[192:195], v[76:79]
	v_mfma_f32_16x16x32_bf16 v[72:75], v[160:163], v[192:195], v[72:75]
	s_setprio 0
	s_barrier
	s_add_i32 s38, 0, 0x1c000
	s_add_i32 s39, s60, s25
	v_add_u32_e32 v212, s38, v147
	v_lshl_add_u64 v[144:145], v[144:145], 0, s[8:9]
	s_mov_b32 m0, s39
	ds_read_b128 v[200:203], v212
	ds_read_b128 v[204:207], v212 offset:1024
	ds_read_b128 v[208:211], v212 offset:2048
	ds_read_b128 v[212:215], v212 offset:3072
	global_load_lds_dwordx4 v[144:145], off
	v_lshl_add_u64 v[144:145], v[196:197], 0, s[8:9]
	s_add_i32 m0, s39, 0x2000
	s_nop 0
	global_load_lds_dwordx4 v[144:145], off
	s_barrier
	s_waitcnt lgkmcnt(0)
	s_setprio 1
	s_waitcnt lgkmcnt(0)
	v_mfma_f32_16x16x32_bf16 v[116:119], v[200:203], v[164:167], v[116:119]
	v_mfma_f32_16x16x32_bf16 v[112:115], v[208:211], v[164:167], v[112:115]
	v_mfma_f32_16x16x32_bf16 v[100:103], v[200:203], v[172:175], v[100:103]
	v_mfma_f32_16x16x32_bf16 v[96:99], v[208:211], v[172:175], v[96:99]
	v_mfma_f32_16x16x32_bf16 v[84:87], v[200:203], v[180:183], v[84:87]
	v_mfma_f32_16x16x32_bf16 v[80:83], v[208:211], v[180:183], v[80:83]
	v_mfma_f32_16x16x32_bf16 v[68:71], v[200:203], v[188:191], v[68:71]
	v_mfma_f32_16x16x32_bf16 v[64:67], v[208:211], v[188:191], v[64:67]
	v_mfma_f32_16x16x32_bf16 v[116:119], v[204:207], v[168:171], v[116:119]
	v_mfma_f32_16x16x32_bf16 v[112:115], v[212:215], v[168:171], v[112:115]
	v_mfma_f32_16x16x32_bf16 v[100:103], v[204:207], v[176:179], v[100:103]
	v_mfma_f32_16x16x32_bf16 v[96:99], v[212:215], v[176:179], v[96:99]
	v_mfma_f32_16x16x32_bf16 v[84:87], v[204:207], v[184:187], v[84:87]
	v_mfma_f32_16x16x32_bf16 v[80:83], v[212:215], v[184:187], v[80:83]
	v_mfma_f32_16x16x32_bf16 v[68:71], v[204:207], v[192:195], v[68:71]
	v_mfma_f32_16x16x32_bf16 v[64:67], v[212:215], v[192:195], v[64:67]
	s_setprio 0
	s_mov_b32 m0, s40
	v_lshl_add_u64 v[144:145], v[216:217], 0, s[8:9]
	s_barrier
	ds_read_b128 v[164:167], v150 offset:49152
	ds_read_b128 v[168:171], v150 offset:50176
	ds_read_b128 v[172:175], v150 offset:51200
	ds_read_b128 v[176:179], v150 offset:52224
	ds_read_b128 v[180:183], v150 offset:53248
	ds_read_b128 v[184:187], v150 offset:54272
	ds_read_b128 v[188:191], v150 offset:55296
	ds_read_b128 v[192:195], v150 offset:56320
	global_load_lds_dwordx4 v[144:145], off
	v_lshl_add_u64 v[144:145], v[218:219], 0, s[8:9]
	s_mov_b32 m0, s41
	s_nop 0
	global_load_lds_dwordx4 v[144:145], off
	s_barrier
	s_waitcnt lgkmcnt(0)
	s_setprio 1
	s_waitcnt lgkmcnt(0)
	v_mfma_f32_16x16x32_bf16 v[60:63], v[140:143], v[164:167], v[60:63]
	v_mfma_f32_16x16x32_bf16 v[56:59], v[156:159], v[164:167], v[56:59]
	v_mfma_f32_16x16x32_bf16 v[44:47], v[140:143], v[172:175], v[44:47]
	v_mfma_f32_16x16x32_bf16 v[40:43], v[156:159], v[172:175], v[40:43]
	v_mfma_f32_16x16x32_bf16 v[28:31], v[140:143], v[180:183], v[28:31]
	v_mfma_f32_16x16x32_bf16 v[24:27], v[156:159], v[180:183], v[24:27]
	v_mfma_f32_16x16x32_bf16 v[12:15], v[140:143], v[188:191], v[12:15]
	v_mfma_f32_16x16x32_bf16 v[8:11], v[156:159], v[188:191], v[8:11]
	v_mfma_f32_16x16x32_bf16 v[60:63], v[152:155], v[168:171], v[60:63]
	v_mfma_f32_16x16x32_bf16 v[56:59], v[160:163], v[168:171], v[56:59]
	v_mfma_f32_16x16x32_bf16 v[44:47], v[152:155], v[176:179], v[44:47]
	v_mfma_f32_16x16x32_bf16 v[40:43], v[160:163], v[176:179], v[40:43]
	v_mfma_f32_16x16x32_bf16 v[28:31], v[152:155], v[184:187], v[28:31]
	v_mfma_f32_16x16x32_bf16 v[24:27], v[160:163], v[184:187], v[24:27]
	v_mfma_f32_16x16x32_bf16 v[12:15], v[152:155], v[192:195], v[12:15]
	v_mfma_f32_16x16x32_bf16 v[8:11], v[160:163], v[192:195], v[8:11]
	s_setprio 0
	s_barrier
	s_add_u32 s36, s36, 0x40080
	s_addc_u32 s37, s37, 0
	s_add_i32 s38, s38, s25
	v_lshl_add_u64 v[140:141], s[36:37], 0, v[130:131]
	s_mov_b32 m0, s38
	s_nop 0
	global_load_lds_dwordx4 v[140:141], off
	v_lshl_add_u64 v[140:141], s[36:37], 0, v[128:129]
	s_add_i32 m0, s38, 0x2000
	s_nop 0
	global_load_lds_dwordx4 v[140:141], off
	s_waitcnt vmcnt(6)
	s_barrier
	s_setprio 1
	v_mfma_f32_16x16x32_bf16 v[52:55], v[200:203], v[164:167], v[52:55]
	v_mfma_f32_16x16x32_bf16 v[48:51], v[208:211], v[164:167], v[48:51]
	v_mfma_f32_16x16x32_bf16 v[36:39], v[200:203], v[172:175], v[36:39]
	v_mfma_f32_16x16x32_bf16 v[32:35], v[208:211], v[172:175], v[32:35]
	v_mfma_f32_16x16x32_bf16 v[20:23], v[200:203], v[180:183], v[20:23]
	v_mfma_f32_16x16x32_bf16 v[16:19], v[208:211], v[180:183], v[16:19]
	v_mfma_f32_16x16x32_bf16 v[4:7], v[200:203], v[188:191], v[4:7]
	v_mfma_f32_16x16x32_bf16 v[0:3], v[208:211], v[188:191], v[0:3]
	v_mfma_f32_16x16x32_bf16 v[52:55], v[204:207], v[168:171], v[52:55]
	v_mfma_f32_16x16x32_bf16 v[48:51], v[212:215], v[168:171], v[48:51]
	v_mfma_f32_16x16x32_bf16 v[36:39], v[204:207], v[176:179], v[36:39]
	v_mfma_f32_16x16x32_bf16 v[32:35], v[212:215], v[176:179], v[32:35]
	v_mfma_f32_16x16x32_bf16 v[20:23], v[204:207], v[184:187], v[20:23]
	v_mfma_f32_16x16x32_bf16 v[16:19], v[212:215], v[184:187], v[16:19]
	v_mfma_f32_16x16x32_bf16 v[4:7], v[204:207], v[192:195], v[4:7]
	v_mfma_f32_16x16x32_bf16 v[0:3], v[212:215], v[192:195], v[0:3]
	s_setprio 0
	s_add_i32 s59, s59, 2
	s_add_u32 s22, s22, 0x100
	s_addc_u32 s23, s23, 0
	s_add_u32 s57, s57, 0x100
	s_addc_u32 s58, s58, 0
	s_cmp_gt_u32 s59, 13
	s_barrier
	s_cbranch_scc0 .LBB0_878
	v_lshl_add_u32 v190, s20, 8, v146
	v_lshl_or_b32 v191, s33, 8, v148
	v_lshl_add_u32 v184, v190, 10, v191
	v_and_b32_e32 v190, 16, v198
	v_lshrrev_b32_e32 v191, 1, v190
	v_add_u32_e32 v190, v190, v191
	v_lshl_add_u32 v176, v184, 1, v190
	v_add_u32_e32 v177, 0x8000, v176
	v_add_u32_e32 v178, 0x10000, v176
	v_add_u32_e32 v179, 0x18000, v176
	v_add_u32_e32 v180, 0x40000, v176
	v_add_u32_e32 v181, 0x48000, v176
	v_add_u32_e32 v182, 0x50000, v176
	v_add_u32_e32 v183, 0x58000, v176
	v_mov_b32_e32 v186, 0xbfb8aa3b
	v_mov_b32_e32 v187, 0xbfb8aa3b
	v_mov_b32_e32 v188, 1.0
	v_mov_b32_e32 v189, 1.0
	s_and_b64 vcc, exec, s[6:7]
	global_load_dwordx4 v[200:203], v176, s[88:89]
	global_load_dwordx4 v[204:207], v176, s[4:5]
	global_load_dwordx4 v[208:211], v176, s[88:89] offset:256
	global_load_dwordx4 v[212:215], v176, s[4:5] offset:256
	global_load_dwordx4 v[216:219], v177, s[88:89]
	global_load_dwordx4 v[220:223], v177, s[4:5]
	global_load_dwordx4 v[224:227], v177, s[88:89] offset:256
	global_load_dwordx4 v[228:231], v177, s[4:5] offset:256
	global_load_dwordx4 v[232:235], v178, s[88:89]
	global_load_dwordx4 v[236:239], v178, s[4:5]
	global_load_dwordx4 v[240:243], v178, s[88:89] offset:256
	global_load_dwordx4 v[244:247], v178, s[4:5] offset:256
	global_load_dwordx4 v[152:155], v179, s[88:89]
	global_load_dwordx4 v[156:159], v179, s[4:5]
	global_load_dwordx4 v[160:163], v179, s[88:89] offset:256
	global_load_dwordx4 v[164:167], v179, s[4:5] offset:256
	v_pk_mul_f32 v[124:125], v[124:125], v[186:187]
	v_pk_mul_f32 v[126:127], v[126:127], v[186:187]
	v_pk_mul_f32 v[120:121], v[120:121], v[186:187]
	v_pk_mul_f32 v[122:123], v[122:123], v[186:187]
	v_exp_f32_e32 v124, v124
	v_exp_f32_e32 v125, v125
	v_exp_f32_e32 v126, v126
	v_exp_f32_e32 v127, v127
	v_exp_f32_e32 v120, v120
	v_exp_f32_e32 v121, v121
	v_exp_f32_e32 v122, v122
	v_exp_f32_e32 v123, v123
	v_pk_add_f32 v[124:125], v[124:125], v[188:189]
	v_pk_add_f32 v[126:127], v[126:127], v[188:189]
	v_pk_add_f32 v[120:121], v[120:121], v[188:189]
	v_pk_add_f32 v[122:123], v[122:123], v[188:189]
	v_rcp_f32_e32 v124, v124
	v_rcp_f32_e32 v125, v125
	v_rcp_f32_e32 v126, v126
	v_rcp_f32_e32 v127, v127
	v_rcp_f32_e32 v120, v120
	v_rcp_f32_e32 v121, v121
	v_rcp_f32_e32 v122, v122
	v_rcp_f32_e32 v123, v123
	s_waitcnt vmcnt(14)
	v_permlane16_swap_b32_e32 v200, v202
	v_permlane16_swap_b32_e32 v201, v203
	v_permlane16_swap_b32_e32 v204, v206
	v_permlane16_swap_b32_e32 v205, v207
	v_lshlrev_b32_e32 v168, 16, v200
	v_and_b32_e32 v169, 0xffff0000, v200
	v_lshlrev_b32_e32 v200, 16, v201
	v_and_b32_e32 v201, 0xffff0000, v201
	v_lshlrev_b32_e32 v170, 16, v202
	v_and_b32_e32 v171, 0xffff0000, v202
	v_lshlrev_b32_e32 v202, 16, v203
	v_and_b32_e32 v203, 0xffff0000, v203
	v_lshlrev_b32_e32 v172, 16, v204
	v_and_b32_e32 v173, 0xffff0000, v204
	v_lshlrev_b32_e32 v204, 16, v205
	v_and_b32_e32 v205, 0xffff0000, v205
	v_lshlrev_b32_e32 v174, 16, v206
	v_and_b32_e32 v175, 0xffff0000, v206
	v_lshlrev_b32_e32 v206, 16, v207
	v_and_b32_e32 v207, 0xffff0000, v207
	v_pk_fma_f32 v[124:125], v[124:125], v[172:173], v[168:169]
	v_pk_fma_f32 v[126:127], v[126:127], v[204:205], v[200:201]
	v_pk_fma_f32 v[120:121], v[120:121], v[174:175], v[170:171]
	v_pk_fma_f32 v[122:123], v[122:123], v[206:207], v[202:203]
	v_cvt_pk_bf16_f32 v168, v124, v125
	v_cvt_pk_bf16_f32 v169, v126, v127
	v_cvt_pk_bf16_f32 v170, v120, v121
	v_cvt_pk_bf16_f32 v171, v122, v123
	s_nop 1
	v_permlane16_swap_b32_e32 v168, v170
	v_permlane16_swap_b32_e32 v169, v171
	global_store_dwordx4 v176, v[168:171], s[0:1]
	global_load_dwordx4 v[200:203], v180, s[88:89]
	global_load_dwordx4 v[204:207], v180, s[4:5]
	v_pk_mul_f32 v[116:117], v[116:117], v[186:187]
	v_pk_mul_f32 v[118:119], v[118:119], v[186:187]
	v_pk_mul_f32 v[112:113], v[112:113], v[186:187]
	v_pk_mul_f32 v[114:115], v[114:115], v[186:187]
	v_exp_f32_e32 v116, v116
	v_exp_f32_e32 v117, v117
	v_exp_f32_e32 v118, v118
	v_exp_f32_e32 v119, v119
	v_exp_f32_e32 v112, v112
	v_exp_f32_e32 v113, v113
	v_exp_f32_e32 v114, v114
	v_exp_f32_e32 v115, v115
	v_pk_add_f32 v[116:117], v[116:117], v[188:189]
	v_pk_add_f32 v[118:119], v[118:119], v[188:189]
	v_pk_add_f32 v[112:113], v[112:113], v[188:189]
	v_pk_add_f32 v[114:115], v[114:115], v[188:189]
	v_rcp_f32_e32 v116, v116
	v_rcp_f32_e32 v117, v117
	v_rcp_f32_e32 v118, v118
	v_rcp_f32_e32 v119, v119
	v_rcp_f32_e32 v112, v112
	v_rcp_f32_e32 v113, v113
	v_rcp_f32_e32 v114, v114
	v_rcp_f32_e32 v115, v115
	s_waitcnt vmcnt(15)
	v_permlane16_swap_b32_e32 v208, v210
	v_permlane16_swap_b32_e32 v209, v211
	v_permlane16_swap_b32_e32 v212, v214
	v_permlane16_swap_b32_e32 v213, v215
	v_lshlrev_b32_e32 v168, 16, v208
	v_and_b32_e32 v169, 0xffff0000, v208
	v_lshlrev_b32_e32 v208, 16, v209
	v_and_b32_e32 v209, 0xffff0000, v209
	v_lshlrev_b32_e32 v170, 16, v210
	v_and_b32_e32 v171, 0xffff0000, v210
	v_lshlrev_b32_e32 v210, 16, v211
	v_and_b32_e32 v211, 0xffff0000, v211
	v_lshlrev_b32_e32 v172, 16, v212
	v_and_b32_e32 v173, 0xffff0000, v212
	v_lshlrev_b32_e32 v212, 16, v213
	v_and_b32_e32 v213, 0xffff0000, v213
	v_lshlrev_b32_e32 v174, 16, v214
	v_and_b32_e32 v175, 0xffff0000, v214
	v_lshlrev_b32_e32 v214, 16, v215
	v_and_b32_e32 v215, 0xffff0000, v215
	v_pk_fma_f32 v[116:117], v[116:117], v[172:173], v[168:169]
	v_pk_fma_f32 v[118:119], v[118:119], v[212:213], v[208:209]
	v_pk_fma_f32 v[112:113], v[112:113], v[174:175], v[170:171]
	v_pk_fma_f32 v[114:115], v[114:115], v[214:215], v[210:211]
	v_cvt_pk_bf16_f32 v168, v116, v117
	v_cvt_pk_bf16_f32 v169, v118, v119
	v_cvt_pk_bf16_f32 v170, v112, v113
	v_cvt_pk_bf16_f32 v171, v114, v115
	s_nop 1
	v_permlane16_swap_b32_e32 v168, v170
	v_permlane16_swap_b32_e32 v169, v171
	global_store_dwordx4 v176, v[168:171], s[0:1] offset:256
	global_load_dwordx4 v[208:211], v180, s[88:89] offset:256
	global_load_dwordx4 v[212:215], v180, s[4:5] offset:256
	v_pk_mul_f32 v[108:109], v[108:109], v[186:187]
	v_pk_mul_f32 v[110:111], v[110:111], v[186:187]
	v_pk_mul_f32 v[104:105], v[104:105], v[186:187]
	v_pk_mul_f32 v[106:107], v[106:107], v[186:187]
	v_exp_f32_e32 v108, v108
	v_exp_f32_e32 v109, v109
	v_exp_f32_e32 v110, v110
	v_exp_f32_e32 v111, v111
	v_exp_f32_e32 v104, v104
	v_exp_f32_e32 v105, v105
	v_exp_f32_e32 v106, v106
	v_exp_f32_e32 v107, v107
	v_pk_add_f32 v[108:109], v[108:109], v[188:189]
	v_pk_add_f32 v[110:111], v[110:111], v[188:189]
	v_pk_add_f32 v[104:105], v[104:105], v[188:189]
	v_pk_add_f32 v[106:107], v[106:107], v[188:189]
	v_rcp_f32_e32 v108, v108
	v_rcp_f32_e32 v109, v109
	v_rcp_f32_e32 v110, v110
	v_rcp_f32_e32 v111, v111
	v_rcp_f32_e32 v104, v104
	v_rcp_f32_e32 v105, v105
	v_rcp_f32_e32 v106, v106
	v_rcp_f32_e32 v107, v107
	s_waitcnt vmcnt(16)
	v_permlane16_swap_b32_e32 v216, v218
	v_permlane16_swap_b32_e32 v217, v219
	v_permlane16_swap_b32_e32 v220, v222
	v_permlane16_swap_b32_e32 v221, v223
	v_lshlrev_b32_e32 v168, 16, v216
	v_and_b32_e32 v169, 0xffff0000, v216
	v_lshlrev_b32_e32 v216, 16, v217
	v_and_b32_e32 v217, 0xffff0000, v217
	v_lshlrev_b32_e32 v170, 16, v218
	v_and_b32_e32 v171, 0xffff0000, v218
	v_lshlrev_b32_e32 v218, 16, v219
	v_and_b32_e32 v219, 0xffff0000, v219
	v_lshlrev_b32_e32 v172, 16, v220
	v_and_b32_e32 v173, 0xffff0000, v220
	v_lshlrev_b32_e32 v220, 16, v221
	v_and_b32_e32 v221, 0xffff0000, v221
	v_lshlrev_b32_e32 v174, 16, v222
	v_and_b32_e32 v175, 0xffff0000, v222
	v_lshlrev_b32_e32 v222, 16, v223
	v_and_b32_e32 v223, 0xffff0000, v223
	v_pk_fma_f32 v[108:109], v[108:109], v[172:173], v[168:169]
	v_pk_fma_f32 v[110:111], v[110:111], v[220:221], v[216:217]
	v_pk_fma_f32 v[104:105], v[104:105], v[174:175], v[170:171]
	v_pk_fma_f32 v[106:107], v[106:107], v[222:223], v[218:219]
	v_cvt_pk_bf16_f32 v168, v108, v109
	v_cvt_pk_bf16_f32 v169, v110, v111
	v_cvt_pk_bf16_f32 v170, v104, v105
	v_cvt_pk_bf16_f32 v171, v106, v107
	s_nop 1
	v_permlane16_swap_b32_e32 v168, v170
	v_permlane16_swap_b32_e32 v169, v171
	global_store_dwordx4 v177, v[168:171], s[0:1]
	global_load_dwordx4 v[216:219], v181, s[88:89]
	global_load_dwordx4 v[220:223], v181, s[4:5]
	v_pk_mul_f32 v[100:101], v[100:101], v[186:187]
	v_pk_mul_f32 v[102:103], v[102:103], v[186:187]
	v_pk_mul_f32 v[96:97], v[96:97], v[186:187]
	v_pk_mul_f32 v[98:99], v[98:99], v[186:187]
	v_exp_f32_e32 v100, v100
	v_exp_f32_e32 v101, v101
	v_exp_f32_e32 v102, v102
	v_exp_f32_e32 v103, v103
	v_exp_f32_e32 v96, v96
	v_exp_f32_e32 v97, v97
	v_exp_f32_e32 v98, v98
	v_exp_f32_e32 v99, v99
	v_pk_add_f32 v[100:101], v[100:101], v[188:189]
	v_pk_add_f32 v[102:103], v[102:103], v[188:189]
	v_pk_add_f32 v[96:97], v[96:97], v[188:189]
	v_pk_add_f32 v[98:99], v[98:99], v[188:189]
	v_rcp_f32_e32 v100, v100
	v_rcp_f32_e32 v101, v101
	v_rcp_f32_e32 v102, v102
	v_rcp_f32_e32 v103, v103
	v_rcp_f32_e32 v96, v96
	v_rcp_f32_e32 v97, v97
	v_rcp_f32_e32 v98, v98
	v_rcp_f32_e32 v99, v99
	s_waitcnt vmcnt(17)
	v_permlane16_swap_b32_e32 v224, v226
	v_permlane16_swap_b32_e32 v225, v227
	v_permlane16_swap_b32_e32 v228, v230
	v_permlane16_swap_b32_e32 v229, v231
	v_lshlrev_b32_e32 v168, 16, v224
	v_and_b32_e32 v169, 0xffff0000, v224
	v_lshlrev_b32_e32 v224, 16, v225
	v_and_b32_e32 v225, 0xffff0000, v225
	v_lshlrev_b32_e32 v170, 16, v226
	v_and_b32_e32 v171, 0xffff0000, v226
	v_lshlrev_b32_e32 v226, 16, v227
	v_and_b32_e32 v227, 0xffff0000, v227
	v_lshlrev_b32_e32 v172, 16, v228
	v_and_b32_e32 v173, 0xffff0000, v228
	v_lshlrev_b32_e32 v228, 16, v229
	v_and_b32_e32 v229, 0xffff0000, v229
	v_lshlrev_b32_e32 v174, 16, v230
	v_and_b32_e32 v175, 0xffff0000, v230
	v_lshlrev_b32_e32 v230, 16, v231
	v_and_b32_e32 v231, 0xffff0000, v231
	v_pk_fma_f32 v[100:101], v[100:101], v[172:173], v[168:169]
	v_pk_fma_f32 v[102:103], v[102:103], v[228:229], v[224:225]
	v_pk_fma_f32 v[96:97], v[96:97], v[174:175], v[170:171]
	v_pk_fma_f32 v[98:99], v[98:99], v[230:231], v[226:227]
	v_cvt_pk_bf16_f32 v168, v100, v101
	v_cvt_pk_bf16_f32 v169, v102, v103
	v_cvt_pk_bf16_f32 v170, v96, v97
	v_cvt_pk_bf16_f32 v171, v98, v99
	s_nop 1
	v_permlane16_swap_b32_e32 v168, v170
	v_permlane16_swap_b32_e32 v169, v171
	global_store_dwordx4 v177, v[168:171], s[0:1] offset:256
	global_load_dwordx4 v[224:227], v181, s[88:89] offset:256
	global_load_dwordx4 v[228:231], v181, s[4:5] offset:256
	v_pk_mul_f32 v[92:93], v[92:93], v[186:187]
	v_pk_mul_f32 v[94:95], v[94:95], v[186:187]
	v_pk_mul_f32 v[88:89], v[88:89], v[186:187]
	v_pk_mul_f32 v[90:91], v[90:91], v[186:187]
	v_exp_f32_e32 v92, v92
	v_exp_f32_e32 v93, v93
	v_exp_f32_e32 v94, v94
	v_exp_f32_e32 v95, v95
	v_exp_f32_e32 v88, v88
	v_exp_f32_e32 v89, v89
	v_exp_f32_e32 v90, v90
	v_exp_f32_e32 v91, v91
	v_pk_add_f32 v[92:93], v[92:93], v[188:189]
	v_pk_add_f32 v[94:95], v[94:95], v[188:189]
	v_pk_add_f32 v[88:89], v[88:89], v[188:189]
	v_pk_add_f32 v[90:91], v[90:91], v[188:189]
	v_rcp_f32_e32 v92, v92
	v_rcp_f32_e32 v93, v93
	v_rcp_f32_e32 v94, v94
	v_rcp_f32_e32 v95, v95
	v_rcp_f32_e32 v88, v88
	v_rcp_f32_e32 v89, v89
	v_rcp_f32_e32 v90, v90
	v_rcp_f32_e32 v91, v91
	s_waitcnt vmcnt(18)
	v_permlane16_swap_b32_e32 v232, v234
	v_permlane16_swap_b32_e32 v233, v235
	v_permlane16_swap_b32_e32 v236, v238
	v_permlane16_swap_b32_e32 v237, v239
	v_lshlrev_b32_e32 v168, 16, v232
	v_and_b32_e32 v169, 0xffff0000, v232
	v_lshlrev_b32_e32 v232, 16, v233
	v_and_b32_e32 v233, 0xffff0000, v233
	v_lshlrev_b32_e32 v170, 16, v234
	v_and_b32_e32 v171, 0xffff0000, v234
	v_lshlrev_b32_e32 v234, 16, v235
	v_and_b32_e32 v235, 0xffff0000, v235
	v_lshlrev_b32_e32 v172, 16, v236
	v_and_b32_e32 v173, 0xffff0000, v236
	v_lshlrev_b32_e32 v236, 16, v237
	v_and_b32_e32 v237, 0xffff0000, v237
	v_lshlrev_b32_e32 v174, 16, v238
	v_and_b32_e32 v175, 0xffff0000, v238
	v_lshlrev_b32_e32 v238, 16, v239
	v_and_b32_e32 v239, 0xffff0000, v239
	v_pk_fma_f32 v[92:93], v[92:93], v[172:173], v[168:169]
	v_pk_fma_f32 v[94:95], v[94:95], v[236:237], v[232:233]
	v_pk_fma_f32 v[88:89], v[88:89], v[174:175], v[170:171]
	v_pk_fma_f32 v[90:91], v[90:91], v[238:239], v[234:235]
	v_cvt_pk_bf16_f32 v168, v92, v93
	v_cvt_pk_bf16_f32 v169, v94, v95
	v_cvt_pk_bf16_f32 v170, v88, v89
	v_cvt_pk_bf16_f32 v171, v90, v91
	s_nop 1
	v_permlane16_swap_b32_e32 v168, v170
	v_permlane16_swap_b32_e32 v169, v171
	global_store_dwordx4 v178, v[168:171], s[0:1]
	global_load_dwordx4 v[232:235], v182, s[88:89]
	global_load_dwordx4 v[236:239], v182, s[4:5]
	v_pk_mul_f32 v[84:85], v[84:85], v[186:187]
	v_pk_mul_f32 v[86:87], v[86:87], v[186:187]
	v_pk_mul_f32 v[80:81], v[80:81], v[186:187]
	v_pk_mul_f32 v[82:83], v[82:83], v[186:187]
	v_exp_f32_e32 v84, v84
	v_exp_f32_e32 v85, v85
	v_exp_f32_e32 v86, v86
	v_exp_f32_e32 v87, v87
	v_exp_f32_e32 v80, v80
	v_exp_f32_e32 v81, v81
	v_exp_f32_e32 v82, v82
	v_exp_f32_e32 v83, v83
	v_pk_add_f32 v[84:85], v[84:85], v[188:189]
	v_pk_add_f32 v[86:87], v[86:87], v[188:189]
	v_pk_add_f32 v[80:81], v[80:81], v[188:189]
	v_pk_add_f32 v[82:83], v[82:83], v[188:189]
	v_rcp_f32_e32 v84, v84
	v_rcp_f32_e32 v85, v85
	v_rcp_f32_e32 v86, v86
	v_rcp_f32_e32 v87, v87
	v_rcp_f32_e32 v80, v80
	v_rcp_f32_e32 v81, v81
	v_rcp_f32_e32 v82, v82
	v_rcp_f32_e32 v83, v83
	s_waitcnt vmcnt(19)
	v_permlane16_swap_b32_e32 v240, v242
	v_permlane16_swap_b32_e32 v241, v243
	v_permlane16_swap_b32_e32 v244, v246
	v_permlane16_swap_b32_e32 v245, v247
	v_lshlrev_b32_e32 v168, 16, v240
	v_and_b32_e32 v169, 0xffff0000, v240
	v_lshlrev_b32_e32 v240, 16, v241
	v_and_b32_e32 v241, 0xffff0000, v241
	v_lshlrev_b32_e32 v170, 16, v242
	v_and_b32_e32 v171, 0xffff0000, v242
	v_lshlrev_b32_e32 v242, 16, v243
	v_and_b32_e32 v243, 0xffff0000, v243
	v_lshlrev_b32_e32 v172, 16, v244
	v_and_b32_e32 v173, 0xffff0000, v244
	v_lshlrev_b32_e32 v244, 16, v245
	v_and_b32_e32 v245, 0xffff0000, v245
	v_lshlrev_b32_e32 v174, 16, v246
	v_and_b32_e32 v175, 0xffff0000, v246
	v_lshlrev_b32_e32 v246, 16, v247
	v_and_b32_e32 v247, 0xffff0000, v247
	v_pk_fma_f32 v[84:85], v[84:85], v[172:173], v[168:169]
	v_pk_fma_f32 v[86:87], v[86:87], v[244:245], v[240:241]
	v_pk_fma_f32 v[80:81], v[80:81], v[174:175], v[170:171]
	v_pk_fma_f32 v[82:83], v[82:83], v[246:247], v[242:243]
	v_cvt_pk_bf16_f32 v168, v84, v85
	v_cvt_pk_bf16_f32 v169, v86, v87
	v_cvt_pk_bf16_f32 v170, v80, v81
	v_cvt_pk_bf16_f32 v171, v82, v83
	s_nop 1
	v_permlane16_swap_b32_e32 v168, v170
	v_permlane16_swap_b32_e32 v169, v171
	global_store_dwordx4 v178, v[168:171], s[0:1] offset:256
	global_load_dwordx4 v[240:243], v182, s[88:89] offset:256
	global_load_dwordx4 v[244:247], v182, s[4:5] offset:256
	v_pk_mul_f32 v[76:77], v[76:77], v[186:187]
	v_pk_mul_f32 v[78:79], v[78:79], v[186:187]
	v_pk_mul_f32 v[72:73], v[72:73], v[186:187]
	v_pk_mul_f32 v[74:75], v[74:75], v[186:187]
	v_exp_f32_e32 v76, v76
	v_exp_f32_e32 v77, v77
	v_exp_f32_e32 v78, v78
	v_exp_f32_e32 v79, v79
	v_exp_f32_e32 v72, v72
	v_exp_f32_e32 v73, v73
	v_exp_f32_e32 v74, v74
	v_exp_f32_e32 v75, v75
	v_pk_add_f32 v[76:77], v[76:77], v[188:189]
	v_pk_add_f32 v[78:79], v[78:79], v[188:189]
	v_pk_add_f32 v[72:73], v[72:73], v[188:189]
	v_pk_add_f32 v[74:75], v[74:75], v[188:189]
	v_rcp_f32_e32 v76, v76
	v_rcp_f32_e32 v77, v77
	v_rcp_f32_e32 v78, v78
	v_rcp_f32_e32 v79, v79
	v_rcp_f32_e32 v72, v72
	v_rcp_f32_e32 v73, v73
	v_rcp_f32_e32 v74, v74
	v_rcp_f32_e32 v75, v75
	s_waitcnt vmcnt(20)
	v_permlane16_swap_b32_e32 v152, v154
	v_permlane16_swap_b32_e32 v153, v155
	v_permlane16_swap_b32_e32 v156, v158
	v_permlane16_swap_b32_e32 v157, v159
	v_lshlrev_b32_e32 v168, 16, v152
	v_and_b32_e32 v169, 0xffff0000, v152
	v_lshlrev_b32_e32 v152, 16, v153
	v_and_b32_e32 v153, 0xffff0000, v153
	v_lshlrev_b32_e32 v170, 16, v154
	v_and_b32_e32 v171, 0xffff0000, v154
	v_lshlrev_b32_e32 v154, 16, v155
	v_and_b32_e32 v155, 0xffff0000, v155
	v_lshlrev_b32_e32 v172, 16, v156
	v_and_b32_e32 v173, 0xffff0000, v156
	v_lshlrev_b32_e32 v156, 16, v157
	v_and_b32_e32 v157, 0xffff0000, v157
	v_lshlrev_b32_e32 v174, 16, v158
	v_and_b32_e32 v175, 0xffff0000, v158
	v_lshlrev_b32_e32 v158, 16, v159
	v_and_b32_e32 v159, 0xffff0000, v159
	v_pk_fma_f32 v[76:77], v[76:77], v[172:173], v[168:169]
	v_pk_fma_f32 v[78:79], v[78:79], v[156:157], v[152:153]
	v_pk_fma_f32 v[72:73], v[72:73], v[174:175], v[170:171]
	v_pk_fma_f32 v[74:75], v[74:75], v[158:159], v[154:155]
	v_cvt_pk_bf16_f32 v168, v76, v77
	v_cvt_pk_bf16_f32 v169, v78, v79
	v_cvt_pk_bf16_f32 v170, v72, v73
	v_cvt_pk_bf16_f32 v171, v74, v75
	s_nop 1
	v_permlane16_swap_b32_e32 v168, v170
	v_permlane16_swap_b32_e32 v169, v171
	global_store_dwordx4 v179, v[168:171], s[0:1]
	global_load_dwordx4 v[152:155], v183, s[88:89]
	global_load_dwordx4 v[156:159], v183, s[4:5]
	v_pk_mul_f32 v[68:69], v[68:69], v[186:187]
	v_pk_mul_f32 v[70:71], v[70:71], v[186:187]
	v_pk_mul_f32 v[64:65], v[64:65], v[186:187]
	v_pk_mul_f32 v[66:67], v[66:67], v[186:187]
	v_exp_f32_e32 v68, v68
	v_exp_f32_e32 v69, v69
	v_exp_f32_e32 v70, v70
	v_exp_f32_e32 v71, v71
	v_exp_f32_e32 v64, v64
	v_exp_f32_e32 v65, v65
	v_exp_f32_e32 v66, v66
	v_exp_f32_e32 v67, v67
	v_pk_add_f32 v[68:69], v[68:69], v[188:189]
	v_pk_add_f32 v[70:71], v[70:71], v[188:189]
	v_pk_add_f32 v[64:65], v[64:65], v[188:189]
	v_pk_add_f32 v[66:67], v[66:67], v[188:189]
	v_rcp_f32_e32 v68, v68
	v_rcp_f32_e32 v69, v69
	v_rcp_f32_e32 v70, v70
	v_rcp_f32_e32 v71, v71
	v_rcp_f32_e32 v64, v64
	v_rcp_f32_e32 v65, v65
	v_rcp_f32_e32 v66, v66
	v_rcp_f32_e32 v67, v67
	s_waitcnt vmcnt(21)
	v_permlane16_swap_b32_e32 v160, v162
	v_permlane16_swap_b32_e32 v161, v163
	v_permlane16_swap_b32_e32 v164, v166
	v_permlane16_swap_b32_e32 v165, v167
	v_lshlrev_b32_e32 v168, 16, v160
	v_and_b32_e32 v169, 0xffff0000, v160
	v_lshlrev_b32_e32 v160, 16, v161
	v_and_b32_e32 v161, 0xffff0000, v161
	v_lshlrev_b32_e32 v170, 16, v162
	v_and_b32_e32 v171, 0xffff0000, v162
	v_lshlrev_b32_e32 v162, 16, v163
	v_and_b32_e32 v163, 0xffff0000, v163
	v_lshlrev_b32_e32 v172, 16, v164
	v_and_b32_e32 v173, 0xffff0000, v164
	v_lshlrev_b32_e32 v164, 16, v165
	v_and_b32_e32 v165, 0xffff0000, v165
	v_lshlrev_b32_e32 v174, 16, v166
	v_and_b32_e32 v175, 0xffff0000, v166
	v_lshlrev_b32_e32 v166, 16, v167
	v_and_b32_e32 v167, 0xffff0000, v167
	v_pk_fma_f32 v[68:69], v[68:69], v[172:173], v[168:169]
	v_pk_fma_f32 v[70:71], v[70:71], v[164:165], v[160:161]
	v_pk_fma_f32 v[64:65], v[64:65], v[174:175], v[170:171]
	v_pk_fma_f32 v[66:67], v[66:67], v[166:167], v[162:163]
	v_cvt_pk_bf16_f32 v168, v68, v69
	v_cvt_pk_bf16_f32 v169, v70, v71
	v_cvt_pk_bf16_f32 v170, v64, v65
	v_cvt_pk_bf16_f32 v171, v66, v67
	s_nop 1
	v_permlane16_swap_b32_e32 v168, v170
	v_permlane16_swap_b32_e32 v169, v171
	global_store_dwordx4 v179, v[168:171], s[0:1] offset:256
	global_load_dwordx4 v[160:163], v183, s[88:89] offset:256
	global_load_dwordx4 v[164:167], v183, s[4:5] offset:256
	s_mov_b32 s33, s10
	s_mov_b32 s20, s14
	s_mov_b64 s[36:37], s[18:19]
	s_mov_b64 s[22:23], s[16:17]
	v_pk_mul_f32 v[60:61], v[60:61], v[186:187]
	v_pk_mul_f32 v[62:63], v[62:63], v[186:187]
	v_pk_mul_f32 v[56:57], v[56:57], v[186:187]
	v_pk_mul_f32 v[58:59], v[58:59], v[186:187]
	v_exp_f32_e32 v60, v60
	v_exp_f32_e32 v61, v61
	v_exp_f32_e32 v62, v62
	v_exp_f32_e32 v63, v63
	v_exp_f32_e32 v56, v56
	v_exp_f32_e32 v57, v57
	v_exp_f32_e32 v58, v58
	v_exp_f32_e32 v59, v59
	v_pk_add_f32 v[60:61], v[60:61], v[188:189]
	v_pk_add_f32 v[62:63], v[62:63], v[188:189]
	v_pk_add_f32 v[56:57], v[56:57], v[188:189]
	v_pk_add_f32 v[58:59], v[58:59], v[188:189]
	v_rcp_f32_e32 v60, v60
	v_rcp_f32_e32 v61, v61
	v_rcp_f32_e32 v62, v62
	v_rcp_f32_e32 v63, v63
	v_rcp_f32_e32 v56, v56
	v_rcp_f32_e32 v57, v57
	v_rcp_f32_e32 v58, v58
	v_rcp_f32_e32 v59, v59
	s_waitcnt vmcnt(21)
	v_permlane16_swap_b32_e32 v200, v202
	v_permlane16_swap_b32_e32 v201, v203
	v_permlane16_swap_b32_e32 v204, v206
	v_permlane16_swap_b32_e32 v205, v207
	v_lshlrev_b32_e32 v168, 16, v200
	v_and_b32_e32 v169, 0xffff0000, v200
	v_lshlrev_b32_e32 v200, 16, v201
	v_and_b32_e32 v201, 0xffff0000, v201
	v_lshlrev_b32_e32 v170, 16, v202
	v_and_b32_e32 v171, 0xffff0000, v202
	v_lshlrev_b32_e32 v202, 16, v203
	v_and_b32_e32 v203, 0xffff0000, v203
	v_lshlrev_b32_e32 v172, 16, v204
	v_and_b32_e32 v173, 0xffff0000, v204
	v_lshlrev_b32_e32 v204, 16, v205
	v_and_b32_e32 v205, 0xffff0000, v205
	v_lshlrev_b32_e32 v174, 16, v206
	v_and_b32_e32 v175, 0xffff0000, v206
	v_lshlrev_b32_e32 v206, 16, v207
	v_and_b32_e32 v207, 0xffff0000, v207
	v_pk_fma_f32 v[60:61], v[60:61], v[172:173], v[168:169]
	v_pk_fma_f32 v[62:63], v[62:63], v[204:205], v[200:201]
	v_pk_fma_f32 v[56:57], v[56:57], v[174:175], v[170:171]
	v_pk_fma_f32 v[58:59], v[58:59], v[206:207], v[202:203]
	v_cvt_pk_bf16_f32 v168, v60, v61
	v_cvt_pk_bf16_f32 v169, v62, v63
	v_cvt_pk_bf16_f32 v170, v56, v57
	v_cvt_pk_bf16_f32 v171, v58, v59
	s_nop 1
	v_permlane16_swap_b32_e32 v168, v170
	v_permlane16_swap_b32_e32 v169, v171
	global_store_dwordx4 v180, v[168:171], s[0:1]
	v_pk_mul_f32 v[52:53], v[52:53], v[186:187]
	v_pk_mul_f32 v[54:55], v[54:55], v[186:187]
	v_pk_mul_f32 v[48:49], v[48:49], v[186:187]
	v_pk_mul_f32 v[50:51], v[50:51], v[186:187]
	v_exp_f32_e32 v52, v52
	v_exp_f32_e32 v53, v53
	v_exp_f32_e32 v54, v54
	v_exp_f32_e32 v55, v55
	v_exp_f32_e32 v48, v48
	v_exp_f32_e32 v49, v49
	v_exp_f32_e32 v50, v50
	v_exp_f32_e32 v51, v51
	v_pk_add_f32 v[52:53], v[52:53], v[188:189]
	v_pk_add_f32 v[54:55], v[54:55], v[188:189]
	v_pk_add_f32 v[48:49], v[48:49], v[188:189]
	v_pk_add_f32 v[50:51], v[50:51], v[188:189]
	v_rcp_f32_e32 v52, v52
	v_rcp_f32_e32 v53, v53
	v_rcp_f32_e32 v54, v54
	v_rcp_f32_e32 v55, v55
	v_rcp_f32_e32 v48, v48
	v_rcp_f32_e32 v49, v49
	v_rcp_f32_e32 v50, v50
	v_rcp_f32_e32 v51, v51
	s_waitcnt vmcnt(19)
	v_permlane16_swap_b32_e32 v208, v210
	v_permlane16_swap_b32_e32 v209, v211
	v_permlane16_swap_b32_e32 v212, v214
	v_permlane16_swap_b32_e32 v213, v215
	v_lshlrev_b32_e32 v168, 16, v208
	v_and_b32_e32 v169, 0xffff0000, v208
	v_lshlrev_b32_e32 v208, 16, v209
	v_and_b32_e32 v209, 0xffff0000, v209
	v_lshlrev_b32_e32 v170, 16, v210
	v_and_b32_e32 v171, 0xffff0000, v210
	v_lshlrev_b32_e32 v210, 16, v211
	v_and_b32_e32 v211, 0xffff0000, v211
	v_lshlrev_b32_e32 v172, 16, v212
	v_and_b32_e32 v173, 0xffff0000, v212
	v_lshlrev_b32_e32 v212, 16, v213
	v_and_b32_e32 v213, 0xffff0000, v213
	v_lshlrev_b32_e32 v174, 16, v214
	v_and_b32_e32 v175, 0xffff0000, v214
	v_lshlrev_b32_e32 v214, 16, v215
	v_and_b32_e32 v215, 0xffff0000, v215
	v_pk_fma_f32 v[52:53], v[52:53], v[172:173], v[168:169]
	v_pk_fma_f32 v[54:55], v[54:55], v[212:213], v[208:209]
	v_pk_fma_f32 v[48:49], v[48:49], v[174:175], v[170:171]
	v_pk_fma_f32 v[50:51], v[50:51], v[214:215], v[210:211]
	v_cvt_pk_bf16_f32 v168, v52, v53
	v_cvt_pk_bf16_f32 v169, v54, v55
	v_cvt_pk_bf16_f32 v170, v48, v49
	v_cvt_pk_bf16_f32 v171, v50, v51
	s_nop 1
	v_permlane16_swap_b32_e32 v168, v170
	v_permlane16_swap_b32_e32 v169, v171
	global_store_dwordx4 v180, v[168:171], s[0:1] offset:256
	v_pk_mul_f32 v[44:45], v[44:45], v[186:187]
	v_pk_mul_f32 v[46:47], v[46:47], v[186:187]
	v_pk_mul_f32 v[40:41], v[40:41], v[186:187]
	v_pk_mul_f32 v[42:43], v[42:43], v[186:187]
	v_exp_f32_e32 v44, v44
	v_exp_f32_e32 v45, v45
	v_exp_f32_e32 v46, v46
	v_exp_f32_e32 v47, v47
	v_exp_f32_e32 v40, v40
	v_exp_f32_e32 v41, v41
	v_exp_f32_e32 v42, v42
	v_exp_f32_e32 v43, v43
	v_pk_add_f32 v[44:45], v[44:45], v[188:189]
	v_pk_add_f32 v[46:47], v[46:47], v[188:189]
	v_pk_add_f32 v[40:41], v[40:41], v[188:189]
	v_pk_add_f32 v[42:43], v[42:43], v[188:189]
	v_rcp_f32_e32 v44, v44
	v_rcp_f32_e32 v45, v45
	v_rcp_f32_e32 v46, v46
	v_rcp_f32_e32 v47, v47
	v_rcp_f32_e32 v40, v40
	v_rcp_f32_e32 v41, v41
	v_rcp_f32_e32 v42, v42
	v_rcp_f32_e32 v43, v43
	s_waitcnt vmcnt(17)
	v_permlane16_swap_b32_e32 v216, v218
	v_permlane16_swap_b32_e32 v217, v219
	v_permlane16_swap_b32_e32 v220, v222
	v_permlane16_swap_b32_e32 v221, v223
	v_lshlrev_b32_e32 v168, 16, v216
	v_and_b32_e32 v169, 0xffff0000, v216
	v_lshlrev_b32_e32 v216, 16, v217
	v_and_b32_e32 v217, 0xffff0000, v217
	v_lshlrev_b32_e32 v170, 16, v218
	v_and_b32_e32 v171, 0xffff0000, v218
	v_lshlrev_b32_e32 v218, 16, v219
	v_and_b32_e32 v219, 0xffff0000, v219
	v_lshlrev_b32_e32 v172, 16, v220
	v_and_b32_e32 v173, 0xffff0000, v220
	v_lshlrev_b32_e32 v220, 16, v221
	v_and_b32_e32 v221, 0xffff0000, v221
	v_lshlrev_b32_e32 v174, 16, v222
	v_and_b32_e32 v175, 0xffff0000, v222
	v_lshlrev_b32_e32 v222, 16, v223
	v_and_b32_e32 v223, 0xffff0000, v223
	v_pk_fma_f32 v[44:45], v[44:45], v[172:173], v[168:169]
	v_pk_fma_f32 v[46:47], v[46:47], v[220:221], v[216:217]
	v_pk_fma_f32 v[40:41], v[40:41], v[174:175], v[170:171]
	v_pk_fma_f32 v[42:43], v[42:43], v[222:223], v[218:219]
	v_cvt_pk_bf16_f32 v168, v44, v45
	v_cvt_pk_bf16_f32 v169, v46, v47
	v_cvt_pk_bf16_f32 v170, v40, v41
	v_cvt_pk_bf16_f32 v171, v42, v43
	s_nop 1
	v_permlane16_swap_b32_e32 v168, v170
	v_permlane16_swap_b32_e32 v169, v171
	global_store_dwordx4 v181, v[168:171], s[0:1]
	v_pk_mul_f32 v[36:37], v[36:37], v[186:187]
	v_pk_mul_f32 v[38:39], v[38:39], v[186:187]
	v_pk_mul_f32 v[32:33], v[32:33], v[186:187]
	v_pk_mul_f32 v[34:35], v[34:35], v[186:187]
	v_exp_f32_e32 v36, v36
	v_exp_f32_e32 v37, v37
	v_exp_f32_e32 v38, v38
	v_exp_f32_e32 v39, v39
	v_exp_f32_e32 v32, v32
	v_exp_f32_e32 v33, v33
	v_exp_f32_e32 v34, v34
	v_exp_f32_e32 v35, v35
	v_pk_add_f32 v[36:37], v[36:37], v[188:189]
	v_pk_add_f32 v[38:39], v[38:39], v[188:189]
	v_pk_add_f32 v[32:33], v[32:33], v[188:189]
	v_pk_add_f32 v[34:35], v[34:35], v[188:189]
	v_rcp_f32_e32 v36, v36
	v_rcp_f32_e32 v37, v37
	v_rcp_f32_e32 v38, v38
	v_rcp_f32_e32 v39, v39
	v_rcp_f32_e32 v32, v32
	v_rcp_f32_e32 v33, v33
	v_rcp_f32_e32 v34, v34
	v_rcp_f32_e32 v35, v35
	s_waitcnt vmcnt(15)
	v_permlane16_swap_b32_e32 v224, v226
	v_permlane16_swap_b32_e32 v225, v227
	v_permlane16_swap_b32_e32 v228, v230
	v_permlane16_swap_b32_e32 v229, v231
	v_lshlrev_b32_e32 v168, 16, v224
	v_and_b32_e32 v169, 0xffff0000, v224
	v_lshlrev_b32_e32 v224, 16, v225
	v_and_b32_e32 v225, 0xffff0000, v225
	v_lshlrev_b32_e32 v170, 16, v226
	v_and_b32_e32 v171, 0xffff0000, v226
	v_lshlrev_b32_e32 v226, 16, v227
	v_and_b32_e32 v227, 0xffff0000, v227
	v_lshlrev_b32_e32 v172, 16, v228
	v_and_b32_e32 v173, 0xffff0000, v228
	v_lshlrev_b32_e32 v228, 16, v229
	v_and_b32_e32 v229, 0xffff0000, v229
	v_lshlrev_b32_e32 v174, 16, v230
	v_and_b32_e32 v175, 0xffff0000, v230
	v_lshlrev_b32_e32 v230, 16, v231
	v_and_b32_e32 v231, 0xffff0000, v231
	v_pk_fma_f32 v[36:37], v[36:37], v[172:173], v[168:169]
	v_pk_fma_f32 v[38:39], v[38:39], v[228:229], v[224:225]
	v_pk_fma_f32 v[32:33], v[32:33], v[174:175], v[170:171]
	v_pk_fma_f32 v[34:35], v[34:35], v[230:231], v[226:227]
	v_cvt_pk_bf16_f32 v168, v36, v37
	v_cvt_pk_bf16_f32 v169, v38, v39
	v_cvt_pk_bf16_f32 v170, v32, v33
	v_cvt_pk_bf16_f32 v171, v34, v35
	s_nop 1
	v_permlane16_swap_b32_e32 v168, v170
	v_permlane16_swap_b32_e32 v169, v171
	global_store_dwordx4 v181, v[168:171], s[0:1] offset:256
	v_pk_mul_f32 v[28:29], v[28:29], v[186:187]
	v_pk_mul_f32 v[30:31], v[30:31], v[186:187]
	v_pk_mul_f32 v[24:25], v[24:25], v[186:187]
	v_pk_mul_f32 v[26:27], v[26:27], v[186:187]
	v_exp_f32_e32 v28, v28
	v_exp_f32_e32 v29, v29
	v_exp_f32_e32 v30, v30
	v_exp_f32_e32 v31, v31
	v_exp_f32_e32 v24, v24
	v_exp_f32_e32 v25, v25
	v_exp_f32_e32 v26, v26
	v_exp_f32_e32 v27, v27
	v_pk_add_f32 v[28:29], v[28:29], v[188:189]
	v_pk_add_f32 v[30:31], v[30:31], v[188:189]
	v_pk_add_f32 v[24:25], v[24:25], v[188:189]
	v_pk_add_f32 v[26:27], v[26:27], v[188:189]
	v_rcp_f32_e32 v28, v28
	v_rcp_f32_e32 v29, v29
	v_rcp_f32_e32 v30, v30
	v_rcp_f32_e32 v31, v31
	v_rcp_f32_e32 v24, v24
	v_rcp_f32_e32 v25, v25
	v_rcp_f32_e32 v26, v26
	v_rcp_f32_e32 v27, v27
	s_waitcnt vmcnt(13)
	v_permlane16_swap_b32_e32 v232, v234
	v_permlane16_swap_b32_e32 v233, v235
	v_permlane16_swap_b32_e32 v236, v238
	v_permlane16_swap_b32_e32 v237, v239
	v_lshlrev_b32_e32 v168, 16, v232
	v_and_b32_e32 v169, 0xffff0000, v232
	v_lshlrev_b32_e32 v232, 16, v233
	v_and_b32_e32 v233, 0xffff0000, v233
	v_lshlrev_b32_e32 v170, 16, v234
	v_and_b32_e32 v171, 0xffff0000, v234
	v_lshlrev_b32_e32 v234, 16, v235
	v_and_b32_e32 v235, 0xffff0000, v235
	v_lshlrev_b32_e32 v172, 16, v236
	v_and_b32_e32 v173, 0xffff0000, v236
	v_lshlrev_b32_e32 v236, 16, v237
	v_and_b32_e32 v237, 0xffff0000, v237
	v_lshlrev_b32_e32 v174, 16, v238
	v_and_b32_e32 v175, 0xffff0000, v238
	v_lshlrev_b32_e32 v238, 16, v239
	v_and_b32_e32 v239, 0xffff0000, v239
	v_pk_fma_f32 v[28:29], v[28:29], v[172:173], v[168:169]
	v_pk_fma_f32 v[30:31], v[30:31], v[236:237], v[232:233]
	v_pk_fma_f32 v[24:25], v[24:25], v[174:175], v[170:171]
	v_pk_fma_f32 v[26:27], v[26:27], v[238:239], v[234:235]
	v_cvt_pk_bf16_f32 v168, v28, v29
	v_cvt_pk_bf16_f32 v169, v30, v31
	v_cvt_pk_bf16_f32 v170, v24, v25
	v_cvt_pk_bf16_f32 v171, v26, v27
	s_nop 1
	v_permlane16_swap_b32_e32 v168, v170
	v_permlane16_swap_b32_e32 v169, v171
	global_store_dwordx4 v182, v[168:171], s[0:1]
	v_pk_mul_f32 v[20:21], v[20:21], v[186:187]
	v_pk_mul_f32 v[22:23], v[22:23], v[186:187]
	v_pk_mul_f32 v[16:17], v[16:17], v[186:187]
	v_pk_mul_f32 v[18:19], v[18:19], v[186:187]
	v_exp_f32_e32 v20, v20
	v_exp_f32_e32 v21, v21
	v_exp_f32_e32 v22, v22
	v_exp_f32_e32 v23, v23
	v_exp_f32_e32 v16, v16
	v_exp_f32_e32 v17, v17
	v_exp_f32_e32 v18, v18
	v_exp_f32_e32 v19, v19
	v_pk_add_f32 v[20:21], v[20:21], v[188:189]
	v_pk_add_f32 v[22:23], v[22:23], v[188:189]
	v_pk_add_f32 v[16:17], v[16:17], v[188:189]
	v_pk_add_f32 v[18:19], v[18:19], v[188:189]
	v_rcp_f32_e32 v20, v20
	v_rcp_f32_e32 v21, v21
	v_rcp_f32_e32 v22, v22
	v_rcp_f32_e32 v23, v23
	v_rcp_f32_e32 v16, v16
	v_rcp_f32_e32 v17, v17
	v_rcp_f32_e32 v18, v18
	v_rcp_f32_e32 v19, v19
	s_waitcnt vmcnt(11)
	v_permlane16_swap_b32_e32 v240, v242
	v_permlane16_swap_b32_e32 v241, v243
	v_permlane16_swap_b32_e32 v244, v246
	v_permlane16_swap_b32_e32 v245, v247
	v_lshlrev_b32_e32 v168, 16, v240
	v_and_b32_e32 v169, 0xffff0000, v240
	v_lshlrev_b32_e32 v240, 16, v241
	v_and_b32_e32 v241, 0xffff0000, v241
	v_lshlrev_b32_e32 v170, 16, v242
	v_and_b32_e32 v171, 0xffff0000, v242
	v_lshlrev_b32_e32 v242, 16, v243
	v_and_b32_e32 v243, 0xffff0000, v243
	v_lshlrev_b32_e32 v172, 16, v244
	v_and_b32_e32 v173, 0xffff0000, v244
	v_lshlrev_b32_e32 v244, 16, v245
	v_and_b32_e32 v245, 0xffff0000, v245
	v_lshlrev_b32_e32 v174, 16, v246
	v_and_b32_e32 v175, 0xffff0000, v246
	v_lshlrev_b32_e32 v246, 16, v247
	v_and_b32_e32 v247, 0xffff0000, v247
	v_pk_fma_f32 v[20:21], v[20:21], v[172:173], v[168:169]
	v_pk_fma_f32 v[22:23], v[22:23], v[244:245], v[240:241]
	v_pk_fma_f32 v[16:17], v[16:17], v[174:175], v[170:171]
	v_pk_fma_f32 v[18:19], v[18:19], v[246:247], v[242:243]
	v_cvt_pk_bf16_f32 v168, v20, v21
	v_cvt_pk_bf16_f32 v169, v22, v23
	v_cvt_pk_bf16_f32 v170, v16, v17
	v_cvt_pk_bf16_f32 v171, v18, v19
	s_nop 1
	v_permlane16_swap_b32_e32 v168, v170
	v_permlane16_swap_b32_e32 v169, v171
	global_store_dwordx4 v182, v[168:171], s[0:1] offset:256
	v_pk_mul_f32 v[12:13], v[12:13], v[186:187]
	v_pk_mul_f32 v[14:15], v[14:15], v[186:187]
	v_pk_mul_f32 v[8:9], v[8:9], v[186:187]
	v_pk_mul_f32 v[10:11], v[10:11], v[186:187]
	v_exp_f32_e32 v12, v12
	v_exp_f32_e32 v13, v13
	v_exp_f32_e32 v14, v14
	v_exp_f32_e32 v15, v15
	v_exp_f32_e32 v8, v8
	v_exp_f32_e32 v9, v9
	v_exp_f32_e32 v10, v10
	v_exp_f32_e32 v11, v11
	v_pk_add_f32 v[12:13], v[12:13], v[188:189]
	v_pk_add_f32 v[14:15], v[14:15], v[188:189]
	v_pk_add_f32 v[8:9], v[8:9], v[188:189]
	v_pk_add_f32 v[10:11], v[10:11], v[188:189]
	v_rcp_f32_e32 v12, v12
	v_rcp_f32_e32 v13, v13
	v_rcp_f32_e32 v14, v14
	v_rcp_f32_e32 v15, v15
	v_rcp_f32_e32 v8, v8
	v_rcp_f32_e32 v9, v9
	v_rcp_f32_e32 v10, v10
	v_rcp_f32_e32 v11, v11
	s_waitcnt vmcnt(9)
	v_permlane16_swap_b32_e32 v152, v154
	v_permlane16_swap_b32_e32 v153, v155
	v_permlane16_swap_b32_e32 v156, v158
	v_permlane16_swap_b32_e32 v157, v159
	v_lshlrev_b32_e32 v168, 16, v152
	v_and_b32_e32 v169, 0xffff0000, v152
	v_lshlrev_b32_e32 v152, 16, v153
	v_and_b32_e32 v153, 0xffff0000, v153
	v_lshlrev_b32_e32 v170, 16, v154
	v_and_b32_e32 v171, 0xffff0000, v154
	v_lshlrev_b32_e32 v154, 16, v155
	v_and_b32_e32 v155, 0xffff0000, v155
	v_lshlrev_b32_e32 v172, 16, v156
	v_and_b32_e32 v173, 0xffff0000, v156
	v_lshlrev_b32_e32 v156, 16, v157
	v_and_b32_e32 v157, 0xffff0000, v157
	v_lshlrev_b32_e32 v174, 16, v158
	v_and_b32_e32 v175, 0xffff0000, v158
	v_lshlrev_b32_e32 v158, 16, v159
	v_and_b32_e32 v159, 0xffff0000, v159
	v_pk_fma_f32 v[12:13], v[12:13], v[172:173], v[168:169]
	v_pk_fma_f32 v[14:15], v[14:15], v[156:157], v[152:153]
	v_pk_fma_f32 v[8:9], v[8:9], v[174:175], v[170:171]
	v_pk_fma_f32 v[10:11], v[10:11], v[158:159], v[154:155]
	v_cvt_pk_bf16_f32 v168, v12, v13
	v_cvt_pk_bf16_f32 v169, v14, v15
	v_cvt_pk_bf16_f32 v170, v8, v9
	v_cvt_pk_bf16_f32 v171, v10, v11
	s_nop 1
	v_permlane16_swap_b32_e32 v168, v170
	v_permlane16_swap_b32_e32 v169, v171
	global_store_dwordx4 v183, v[168:171], s[0:1]
	v_pk_mul_f32 v[4:5], v[4:5], v[186:187]
	v_pk_mul_f32 v[6:7], v[6:7], v[186:187]
	v_pk_mul_f32 v[0:1], v[0:1], v[186:187]
	v_pk_mul_f32 v[2:3], v[2:3], v[186:187]
	v_exp_f32_e32 v4, v4
	v_exp_f32_e32 v5, v5
	v_exp_f32_e32 v6, v6
	v_exp_f32_e32 v7, v7
	v_exp_f32_e32 v0, v0
	v_exp_f32_e32 v1, v1
	v_exp_f32_e32 v2, v2
	v_exp_f32_e32 v3, v3
	v_pk_add_f32 v[4:5], v[4:5], v[188:189]
	v_pk_add_f32 v[6:7], v[6:7], v[188:189]
	v_pk_add_f32 v[0:1], v[0:1], v[188:189]
	v_pk_add_f32 v[2:3], v[2:3], v[188:189]
	v_rcp_f32_e32 v4, v4
	v_rcp_f32_e32 v5, v5
	v_rcp_f32_e32 v6, v6
	v_rcp_f32_e32 v7, v7
	v_rcp_f32_e32 v0, v0
	v_rcp_f32_e32 v1, v1
	v_rcp_f32_e32 v2, v2
	v_rcp_f32_e32 v3, v3
	s_waitcnt vmcnt(7)
	v_permlane16_swap_b32_e32 v160, v162
	v_permlane16_swap_b32_e32 v161, v163
	v_permlane16_swap_b32_e32 v164, v166
	v_permlane16_swap_b32_e32 v165, v167
	v_lshlrev_b32_e32 v168, 16, v160
	v_and_b32_e32 v169, 0xffff0000, v160
	v_lshlrev_b32_e32 v160, 16, v161
	v_and_b32_e32 v161, 0xffff0000, v161
	v_lshlrev_b32_e32 v170, 16, v162
	v_and_b32_e32 v171, 0xffff0000, v162
	v_lshlrev_b32_e32 v162, 16, v163
	v_and_b32_e32 v163, 0xffff0000, v163
	v_lshlrev_b32_e32 v172, 16, v164
	v_and_b32_e32 v173, 0xffff0000, v164
	v_lshlrev_b32_e32 v164, 16, v165
	v_and_b32_e32 v165, 0xffff0000, v165
	v_lshlrev_b32_e32 v174, 16, v166
	v_and_b32_e32 v175, 0xffff0000, v166
	v_lshlrev_b32_e32 v166, 16, v167
	v_and_b32_e32 v167, 0xffff0000, v167
	v_pk_fma_f32 v[4:5], v[4:5], v[172:173], v[168:169]
	v_pk_fma_f32 v[6:7], v[6:7], v[164:165], v[160:161]
	v_pk_fma_f32 v[0:1], v[0:1], v[174:175], v[170:171]
	v_pk_fma_f32 v[2:3], v[2:3], v[166:167], v[162:163]
	v_cvt_pk_bf16_f32 v168, v4, v5
	v_cvt_pk_bf16_f32 v169, v6, v7
	v_cvt_pk_bf16_f32 v170, v0, v1
	v_cvt_pk_bf16_f32 v171, v2, v3
	s_nop 1
	v_permlane16_swap_b32_e32 v168, v170
	v_permlane16_swap_b32_e32 v169, v171
	global_store_dwordx4 v183, v[168:171], s[0:1] offset:256
	s_cbranch_vccz .LBB0_871
	s_waitcnt vmcnt(0)
	s_cmpk_gt_u32 s24, 0xff
	s_cbranch_scc1 .LBB0_882
	s_barrier

.LBB0_1614:
	ds_read_b128 v[140:143], v149
	ds_read_b128 v[152:155], v149 offset:1024
	ds_read_b128 v[156:159], v149 offset:2048
	ds_read_b128 v[160:163], v149 offset:3072
	s_add_u32 s28, s26, 0xfffc0080
	s_addc_u32 s29, s27, -1
	s_cmp_eq_u32 s48, 12
	s_cselect_b32 s31, s17, s29
	s_cselect_b32 s30, s19, s28
	s_cselect_b32 s29, s44, s47
	s_cselect_b32 s28, s45, s46
	v_lshl_add_u64 v[144:145], s[26:27], 0, v[132:133]
	s_add_i32 m0, s25, 0xc000
	ds_read_b128 v[164:167], v150
	ds_read_b128 v[168:171], v150 offset:1024
	ds_read_b128 v[172:175], v150 offset:2048
	ds_read_b128 v[176:179], v150 offset:3072
	ds_read_b128 v[180:183], v150 offset:4096
	ds_read_b128 v[184:187], v150 offset:5120
	ds_read_b128 v[188:191], v150 offset:6144
	ds_read_b128 v[192:195], v150 offset:7168
	global_load_lds_dwordx4 v[144:145], off
	v_lshl_add_u64 v[144:145], s[26:27], 0, v[134:135]
	s_add_i32 m0, s25, 0xe000
	s_nop 0
	global_load_lds_dwordx4 v[144:145], off
	s_waitcnt lgkmcnt(8)
	s_barrier
	s_waitcnt lgkmcnt(0)
	s_setprio 1
	s_waitcnt lgkmcnt(0)
	v_mfma_f32_16x16x32_bf16 v[124:127], v[140:143], v[164:167], v[124:127]
	v_mfma_f32_16x16x32_bf16 v[120:123], v[156:159], v[164:167], v[120:123]
	v_mfma_f32_16x16x32_bf16 v[108:111], v[140:143], v[172:175], v[108:111]
	v_mfma_f32_16x16x32_bf16 v[104:107], v[156:159], v[172:175], v[104:107]
	v_mfma_f32_16x16x32_bf16 v[92:95], v[140:143], v[180:183], v[92:95]
	v_mfma_f32_16x16x32_bf16 v[88:91], v[156:159], v[180:183], v[88:91]
	v_mfma_f32_16x16x32_bf16 v[76:79], v[140:143], v[188:191], v[76:79]
	v_mfma_f32_16x16x32_bf16 v[72:75], v[156:159], v[188:191], v[72:75]
	v_mfma_f32_16x16x32_bf16 v[124:127], v[152:155], v[168:171], v[124:127]
	v_mfma_f32_16x16x32_bf16 v[120:123], v[160:163], v[168:171], v[120:123]
	v_mfma_f32_16x16x32_bf16 v[108:111], v[152:155], v[176:179], v[108:111]
	v_mfma_f32_16x16x32_bf16 v[104:107], v[160:163], v[176:179], v[104:107]
	v_mfma_f32_16x16x32_bf16 v[92:95], v[152:155], v[184:187], v[92:95]
	v_mfma_f32_16x16x32_bf16 v[88:91], v[160:163], v[184:187], v[88:91]
	v_mfma_f32_16x16x32_bf16 v[76:79], v[152:155], v[192:195], v[76:79]
	v_mfma_f32_16x16x32_bf16 v[72:75], v[160:163], v[192:195], v[72:75]
	s_setprio 0
	s_barrier
	s_add_i32 s49, s42, s35
	v_lshl_add_u64 v[144:145], s[28:29], 0, v[130:131]
	s_mov_b32 m0, s49
	ds_read_b128 v[200:203], v151
	ds_read_b128 v[204:207], v151 offset:1024
	ds_read_b128 v[208:211], v151 offset:2048
	ds_read_b128 v[212:215], v151 offset:3072
	global_load_lds_dwordx4 v[144:145], off
	v_lshl_add_u64 v[196:197], s[28:29], 0, v[128:129]
	s_add_i32 m0, s49, 0x2000
	s_nop 0
	global_load_lds_dwordx4 v[196:197], off
	s_barrier
	s_waitcnt lgkmcnt(0)
	s_setprio 1
	s_waitcnt lgkmcnt(0)
	v_mfma_f32_16x16x32_bf16 v[116:119], v[200:203], v[164:167], v[116:119]
	v_mfma_f32_16x16x32_bf16 v[112:115], v[208:211], v[164:167], v[112:115]
	v_mfma_f32_16x16x32_bf16 v[100:103], v[200:203], v[172:175], v[100:103]
	v_mfma_f32_16x16x32_bf16 v[96:99], v[208:211], v[172:175], v[96:99]
	v_mfma_f32_16x16x32_bf16 v[84:87], v[200:203], v[180:183], v[84:87]
	v_mfma_f32_16x16x32_bf16 v[80:83], v[208:211], v[180:183], v[80:83]
	v_mfma_f32_16x16x32_bf16 v[68:71], v[200:203], v[188:191], v[68:71]
	v_mfma_f32_16x16x32_bf16 v[64:67], v[208:211], v[188:191], v[64:67]
	v_mfma_f32_16x16x32_bf16 v[116:119], v[204:207], v[168:171], v[116:119]
	v_mfma_f32_16x16x32_bf16 v[112:115], v[212:215], v[168:171], v[112:115]
	v_mfma_f32_16x16x32_bf16 v[100:103], v[204:207], v[176:179], v[100:103]
	v_mfma_f32_16x16x32_bf16 v[96:99], v[212:215], v[176:179], v[96:99]
	v_mfma_f32_16x16x32_bf16 v[84:87], v[204:207], v[184:187], v[84:87]
	v_mfma_f32_16x16x32_bf16 v[80:83], v[212:215], v[184:187], v[80:83]
	v_mfma_f32_16x16x32_bf16 v[68:71], v[204:207], v[192:195], v[68:71]
	v_mfma_f32_16x16x32_bf16 v[64:67], v[212:215], v[192:195], v[64:67]
	s_setprio 0
	s_mov_b32 m0, s25
	v_lshl_add_u64 v[216:217], s[30:31], 0, v[130:131]
	s_barrier
	ds_read_b128 v[164:167], v150 offset:16384
	ds_read_b128 v[168:171], v150 offset:17408
	ds_read_b128 v[172:175], v150 offset:18432
	ds_read_b128 v[176:179], v150 offset:19456
	ds_read_b128 v[180:183], v150 offset:20480
	ds_read_b128 v[184:187], v150 offset:21504
	ds_read_b128 v[188:191], v150 offset:22528
	ds_read_b128 v[192:195], v150 offset:23552
	global_load_lds_dwordx4 v[216:217], off
	v_lshl_add_u64 v[218:219], s[30:31], 0, v[128:129]
	s_mov_b32 m0, s36
	s_nop 0
	global_load_lds_dwordx4 v[218:219], off
	s_barrier
	s_waitcnt lgkmcnt(0)
	s_setprio 1
	s_waitcnt lgkmcnt(0)
	v_mfma_f32_16x16x32_bf16 v[60:63], v[140:143], v[164:167], v[60:63]
	v_mfma_f32_16x16x32_bf16 v[56:59], v[156:159], v[164:167], v[56:59]
	v_mfma_f32_16x16x32_bf16 v[44:47], v[140:143], v[172:175], v[44:47]
	v_mfma_f32_16x16x32_bf16 v[40:43], v[156:159], v[172:175], v[40:43]
	v_mfma_f32_16x16x32_bf16 v[28:31], v[140:143], v[180:183], v[28:31]
	v_mfma_f32_16x16x32_bf16 v[24:27], v[156:159], v[180:183], v[24:27]
	v_mfma_f32_16x16x32_bf16 v[12:15], v[140:143], v[188:191], v[12:15]
	v_mfma_f32_16x16x32_bf16 v[8:11], v[156:159], v[188:191], v[8:11]
	v_mfma_f32_16x16x32_bf16 v[60:63], v[152:155], v[168:171], v[60:63]
	v_mfma_f32_16x16x32_bf16 v[56:59], v[160:163], v[168:171], v[56:59]
	v_mfma_f32_16x16x32_bf16 v[44:47], v[152:155], v[176:179], v[44:47]
	v_mfma_f32_16x16x32_bf16 v[40:43], v[160:163], v[176:179], v[40:43]
	v_mfma_f32_16x16x32_bf16 v[28:31], v[152:155], v[184:187], v[28:31]
	v_mfma_f32_16x16x32_bf16 v[24:27], v[160:163], v[184:187], v[24:27]
	v_mfma_f32_16x16x32_bf16 v[12:15], v[152:155], v[192:195], v[12:15]
	v_mfma_f32_16x16x32_bf16 v[8:11], v[160:163], v[192:195], v[8:11]
	s_setprio 0
	s_barrier
	s_add_u32 s50, s28, 0x40000
	s_addc_u32 s51, s29, 0
	s_add_i32 s49, s43, s35
	v_lshl_add_u64 v[140:141], s[50:51], 0, v[130:131]
	s_mov_b32 m0, s49
	s_nop 0
	global_load_lds_dwordx4 v[140:141], off
	v_lshl_add_u64 v[140:141], s[50:51], 0, v[128:129]
	s_add_i32 m0, s49, 0x2000
	s_nop 0
	global_load_lds_dwordx4 v[140:141], off
	s_waitcnt vmcnt(6)
	s_barrier
	s_setprio 1
	v_mfma_f32_16x16x32_bf16 v[52:55], v[200:203], v[164:167], v[52:55]
	v_mfma_f32_16x16x32_bf16 v[48:51], v[208:211], v[164:167], v[48:51]
	v_mfma_f32_16x16x32_bf16 v[36:39], v[200:203], v[172:175], v[36:39]
	v_mfma_f32_16x16x32_bf16 v[32:35], v[208:211], v[172:175], v[32:35]
	v_mfma_f32_16x16x32_bf16 v[20:23], v[200:203], v[180:183], v[20:23]
	v_mfma_f32_16x16x32_bf16 v[16:19], v[208:211], v[180:183], v[16:19]
	v_mfma_f32_16x16x32_bf16 v[4:7], v[200:203], v[188:191], v[4:7]
	v_mfma_f32_16x16x32_bf16 v[0:3], v[208:211], v[188:191], v[0:3]
	v_mfma_f32_16x16x32_bf16 v[52:55], v[204:207], v[168:171], v[52:55]
	v_mfma_f32_16x16x32_bf16 v[48:51], v[212:215], v[168:171], v[48:51]
	v_mfma_f32_16x16x32_bf16 v[36:39], v[204:207], v[176:179], v[36:39]
	v_mfma_f32_16x16x32_bf16 v[32:35], v[212:215], v[176:179], v[32:35]
	v_mfma_f32_16x16x32_bf16 v[20:23], v[204:207], v[184:187], v[20:23]
	v_mfma_f32_16x16x32_bf16 v[16:19], v[212:215], v[184:187], v[16:19]
	v_mfma_f32_16x16x32_bf16 v[4:7], v[204:207], v[192:195], v[4:7]
	v_mfma_f32_16x16x32_bf16 v[0:3], v[212:215], v[192:195], v[0:3]
	s_setprio 0
	s_add_i32 s49, 0, 0x18000
	v_add_u32_e32 v160, s49, v147
	s_barrier
	ds_read_b128 v[140:143], v160
	ds_read_b128 v[152:155], v160 offset:1024
	ds_read_b128 v[156:159], v160 offset:2048
	ds_read_b128 v[160:163], v160 offset:3072
	s_add_u32 s30, s30, 0x40000
	s_addc_u32 s31, s31, 0
	s_mov_b32 m0, s37
	v_lshl_add_u64 v[200:201], s[30:31], 0, v[130:131]
	ds_read_b128 v[164:167], v150 offset:32768
	ds_read_b128 v[168:171], v150 offset:33792
	ds_read_b128 v[172:175], v150 offset:34816
	ds_read_b128 v[176:179], v150 offset:35840
	ds_read_b128 v[180:183], v150 offset:36864
	ds_read_b128 v[184:187], v150 offset:37888
	ds_read_b128 v[188:191], v150 offset:38912
	ds_read_b128 v[192:195], v150 offset:39936
	global_load_lds_dwordx4 v[200:201], off
	v_lshl_add_u64 v[200:201], s[30:31], 0, v[128:129]
	s_mov_b32 m0, s38
	s_nop 0
	global_load_lds_dwordx4 v[200:201], off
	s_waitcnt lgkmcnt(8)
	s_barrier
	s_waitcnt lgkmcnt(0)
	s_setprio 1
	s_waitcnt lgkmcnt(0)
	v_mfma_f32_16x16x32_bf16 v[124:127], v[140:143], v[164:167], v[124:127]
	v_mfma_f32_16x16x32_bf16 v[120:123], v[156:159], v[164:167], v[120:123]
	v_mfma_f32_16x16x32_bf16 v[108:111], v[140:143], v[172:175], v[108:111]
	v_mfma_f32_16x16x32_bf16 v[104:107], v[156:159], v[172:175], v[104:107]
	v_mfma_f32_16x16x32_bf16 v[92:95], v[140:143], v[180:183], v[92:95]
	v_mfma_f32_16x16x32_bf16 v[88:91], v[156:159], v[180:183], v[88:91]
	v_mfma_f32_16x16x32_bf16 v[76:79], v[140:143], v[188:191], v[76:79]
	v_mfma_f32_16x16x32_bf16 v[72:75], v[156:159], v[188:191], v[72:75]
	v_mfma_f32_16x16x32_bf16 v[124:127], v[152:155], v[168:171], v[124:127]
	v_mfma_f32_16x16x32_bf16 v[120:123], v[160:163], v[168:171], v[120:123]
	v_mfma_f32_16x16x32_bf16 v[108:111], v[152:155], v[176:179], v[108:111]
	v_mfma_f32_16x16x32_bf16 v[104:107], v[160:163], v[176:179], v[104:107]
	v_mfma_f32_16x16x32_bf16 v[92:95], v[152:155], v[184:187], v[92:95]
	v_mfma_f32_16x16x32_bf16 v[88:91], v[160:163], v[184:187], v[88:91]
	v_mfma_f32_16x16x32_bf16 v[76:79], v[152:155], v[192:195], v[76:79]
	v_mfma_f32_16x16x32_bf16 v[72:75], v[160:163], v[192:195], v[72:75]
	s_setprio 0
	s_barrier
	s_add_i32 s30, 0, 0x1c000
	s_add_i32 s31, s49, s35
	v_add_u32_e32 v199, s30, v147
	v_lshl_add_u64 v[144:145], v[144:145], 0, s[6:7]
	s_mov_b32 m0, s31
	ds_read_b128 v[200:203], v199
	ds_read_b128 v[204:207], v199 offset:1024
	ds_read_b128 v[208:211], v199 offset:2048
	ds_read_b128 v[212:215], v199 offset:3072
	global_load_lds_dwordx4 v[144:145], off
	v_lshl_add_u64 v[144:145], v[196:197], 0, s[6:7]
	s_add_i32 m0, s31, 0x2000
	s_nop 0
	global_load_lds_dwordx4 v[144:145], off
	s_barrier
	s_waitcnt lgkmcnt(0)
	s_setprio 1
	s_waitcnt lgkmcnt(0)
	v_mfma_f32_16x16x32_bf16 v[116:119], v[200:203], v[164:167], v[116:119]
	v_mfma_f32_16x16x32_bf16 v[112:115], v[208:211], v[164:167], v[112:115]
	v_mfma_f32_16x16x32_bf16 v[100:103], v[200:203], v[172:175], v[100:103]
	v_mfma_f32_16x16x32_bf16 v[96:99], v[208:211], v[172:175], v[96:99]
	v_mfma_f32_16x16x32_bf16 v[84:87], v[200:203], v[180:183], v[84:87]
	v_mfma_f32_16x16x32_bf16 v[80:83], v[208:211], v[180:183], v[80:83]
	v_mfma_f32_16x16x32_bf16 v[68:71], v[200:203], v[188:191], v[68:71]
	v_mfma_f32_16x16x32_bf16 v[64:67], v[208:211], v[188:191], v[64:67]
	v_mfma_f32_16x16x32_bf16 v[116:119], v[204:207], v[168:171], v[116:119]
	v_mfma_f32_16x16x32_bf16 v[112:115], v[212:215], v[168:171], v[112:115]
	v_mfma_f32_16x16x32_bf16 v[100:103], v[204:207], v[176:179], v[100:103]
	v_mfma_f32_16x16x32_bf16 v[96:99], v[212:215], v[176:179], v[96:99]
	v_mfma_f32_16x16x32_bf16 v[84:87], v[204:207], v[184:187], v[84:87]
	v_mfma_f32_16x16x32_bf16 v[80:83], v[212:215], v[184:187], v[80:83]
	v_mfma_f32_16x16x32_bf16 v[68:71], v[204:207], v[192:195], v[68:71]
	v_mfma_f32_16x16x32_bf16 v[64:67], v[212:215], v[192:195], v[64:67]
	s_setprio 0
	s_mov_b32 m0, s40
	v_lshl_add_u64 v[144:145], v[216:217], 0, s[6:7]
	s_barrier
	ds_read_b128 v[164:167], v150 offset:49152
	ds_read_b128 v[168:171], v150 offset:50176
	ds_read_b128 v[172:175], v150 offset:51200
	ds_read_b128 v[176:179], v150 offset:52224
	ds_read_b128 v[180:183], v150 offset:53248
	ds_read_b128 v[184:187], v150 offset:54272
	ds_read_b128 v[188:191], v150 offset:55296
	ds_read_b128 v[192:195], v150 offset:56320
	global_load_lds_dwordx4 v[144:145], off
	v_lshl_add_u64 v[144:145], v[218:219], 0, s[6:7]
	s_mov_b32 m0, s41
	s_nop 0
	global_load_lds_dwordx4 v[144:145], off
	s_barrier
	s_waitcnt lgkmcnt(0)
	s_setprio 1
	s_waitcnt lgkmcnt(0)
	v_mfma_f32_16x16x32_bf16 v[60:63], v[140:143], v[164:167], v[60:63]
	v_mfma_f32_16x16x32_bf16 v[56:59], v[156:159], v[164:167], v[56:59]
	v_mfma_f32_16x16x32_bf16 v[44:47], v[140:143], v[172:175], v[44:47]
	v_mfma_f32_16x16x32_bf16 v[40:43], v[156:159], v[172:175], v[40:43]
	v_mfma_f32_16x16x32_bf16 v[28:31], v[140:143], v[180:183], v[28:31]
	v_mfma_f32_16x16x32_bf16 v[24:27], v[156:159], v[180:183], v[24:27]
	v_mfma_f32_16x16x32_bf16 v[12:15], v[140:143], v[188:191], v[12:15]
	v_mfma_f32_16x16x32_bf16 v[8:11], v[156:159], v[188:191], v[8:11]
	v_mfma_f32_16x16x32_bf16 v[60:63], v[152:155], v[168:171], v[60:63]
	v_mfma_f32_16x16x32_bf16 v[56:59], v[160:163], v[168:171], v[56:59]
	v_mfma_f32_16x16x32_bf16 v[44:47], v[152:155], v[176:179], v[44:47]
	v_mfma_f32_16x16x32_bf16 v[40:43], v[160:163], v[176:179], v[40:43]
	v_mfma_f32_16x16x32_bf16 v[28:31], v[152:155], v[184:187], v[28:31]
	v_mfma_f32_16x16x32_bf16 v[24:27], v[160:163], v[184:187], v[24:27]
	v_mfma_f32_16x16x32_bf16 v[12:15], v[152:155], v[192:195], v[12:15]
	v_mfma_f32_16x16x32_bf16 v[8:11], v[160:163], v[192:195], v[8:11]
	s_setprio 0
	s_barrier
	s_add_u32 s28, s28, 0x40080
	s_addc_u32 s29, s29, 0
	s_add_i32 s30, s30, s35
	v_lshl_add_u64 v[140:141], s[28:29], 0, v[130:131]
	s_mov_b32 m0, s30
	s_nop 0
	global_load_lds_dwordx4 v[140:141], off
	v_lshl_add_u64 v[140:141], s[28:29], 0, v[128:129]
	s_add_i32 m0, s30, 0x2000
	s_nop 0
	global_load_lds_dwordx4 v[140:141], off
	s_waitcnt vmcnt(6)
	s_barrier
	s_setprio 1
	v_mfma_f32_16x16x32_bf16 v[52:55], v[200:203], v[164:167], v[52:55]
	v_mfma_f32_16x16x32_bf16 v[48:51], v[208:211], v[164:167], v[48:51]
	v_mfma_f32_16x16x32_bf16 v[36:39], v[200:203], v[172:175], v[36:39]
	v_mfma_f32_16x16x32_bf16 v[32:35], v[208:211], v[172:175], v[32:35]
	v_mfma_f32_16x16x32_bf16 v[20:23], v[200:203], v[180:183], v[20:23]
	v_mfma_f32_16x16x32_bf16 v[16:19], v[208:211], v[180:183], v[16:19]
	v_mfma_f32_16x16x32_bf16 v[4:7], v[200:203], v[188:191], v[4:7]
	v_mfma_f32_16x16x32_bf16 v[0:3], v[208:211], v[188:191], v[0:3]
	v_mfma_f32_16x16x32_bf16 v[52:55], v[204:207], v[168:171], v[52:55]
	v_mfma_f32_16x16x32_bf16 v[48:51], v[212:215], v[168:171], v[48:51]
	v_mfma_f32_16x16x32_bf16 v[36:39], v[204:207], v[176:179], v[36:39]
	v_mfma_f32_16x16x32_bf16 v[32:35], v[212:215], v[176:179], v[32:35]
	v_mfma_f32_16x16x32_bf16 v[20:23], v[204:207], v[184:187], v[20:23]
	v_mfma_f32_16x16x32_bf16 v[16:19], v[212:215], v[184:187], v[16:19]
	v_mfma_f32_16x16x32_bf16 v[4:7], v[204:207], v[192:195], v[4:7]
	v_mfma_f32_16x16x32_bf16 v[0:3], v[212:215], v[192:195], v[0:3]
	s_setprio 0
	s_add_i32 s48, s48, 2
	s_add_u32 s26, s26, 0x100
	s_addc_u32 s27, s27, 0
	s_add_u32 s46, s46, 0x100
	s_addc_u32 s47, s47, 0
	s_cmp_gt_u32 s48, 13
	s_barrier
	s_cbranch_scc0 .LBB0_1614
	v_lshl_add_u32 v190, s24, 8, v146
	v_lshl_or_b32 v191, s33, 8, v148
	v_lshl_add_u32 v184, v190, 10, v191
	v_and_b32_e32 v190, 16, v198
	v_lshrrev_b32_e32 v191, 1, v190
	v_add_u32_e32 v190, v190, v191
	v_lshl_add_u32 v176, v184, 1, v190
	v_add_u32_e32 v177, 0x8000, v176
	v_add_u32_e32 v178, 0x10000, v176
	v_add_u32_e32 v179, 0x18000, v176
	v_add_u32_e32 v180, 0x40000, v176
	v_add_u32_e32 v181, 0x48000, v176
	v_add_u32_e32 v182, 0x50000, v176
	v_add_u32_e32 v183, 0x58000, v176
	v_lshlrev_b32_e32 v184, 2, v184
	v_mov_b32_e32 v186, 0xbfb8aa3b
	v_mov_b32_e32 v187, 0xbfb8aa3b
	v_mov_b32_e32 v188, 1.0
	v_mov_b32_e32 v189, 1.0
	s_and_b64 vcc, exec, s[0:1]
	global_load_dwordx4 v[200:203], v176, s[88:89]
	global_load_dwordx4 v[204:207], v176, s[4:5]
	global_load_dwordx4 v[208:211], v176, s[88:89] offset:256
	global_load_dwordx4 v[212:215], v176, s[4:5] offset:256
	global_load_dwordx4 v[216:219], v177, s[88:89]
	global_load_dwordx4 v[220:223], v177, s[4:5]
	global_load_dwordx4 v[224:227], v177, s[88:89] offset:256
	global_load_dwordx4 v[228:231], v177, s[4:5] offset:256
	global_load_dwordx4 v[232:235], v178, s[88:89]
	global_load_dwordx4 v[236:239], v178, s[4:5]
	global_load_dwordx4 v[240:243], v178, s[88:89] offset:256
	global_load_dwordx4 v[244:247], v178, s[4:5] offset:256
	global_load_dwordx4 v[152:155], v179, s[88:89]
	global_load_dwordx4 v[156:159], v179, s[4:5]
	global_load_dwordx4 v[160:163], v179, s[88:89] offset:256
	global_load_dwordx4 v[164:167], v179, s[4:5] offset:256
	v_pk_mul_f32 v[124:125], v[124:125], v[186:187]
	v_pk_mul_f32 v[126:127], v[126:127], v[186:187]
	v_pk_mul_f32 v[120:121], v[120:121], v[186:187]
	v_pk_mul_f32 v[122:123], v[122:123], v[186:187]
	v_exp_f32_e32 v124, v124
	v_exp_f32_e32 v125, v125
	v_exp_f32_e32 v126, v126
	v_exp_f32_e32 v127, v127
	v_exp_f32_e32 v120, v120
	v_exp_f32_e32 v121, v121
	v_exp_f32_e32 v122, v122
	v_exp_f32_e32 v123, v123
	v_pk_add_f32 v[124:125], v[124:125], v[188:189]
	v_pk_add_f32 v[126:127], v[126:127], v[188:189]
	v_pk_add_f32 v[120:121], v[120:121], v[188:189]
	v_pk_add_f32 v[122:123], v[122:123], v[188:189]
	v_rcp_f32_e32 v124, v124
	v_rcp_f32_e32 v125, v125
	v_rcp_f32_e32 v126, v126
	v_rcp_f32_e32 v127, v127
	v_rcp_f32_e32 v120, v120
	v_rcp_f32_e32 v121, v121
	v_rcp_f32_e32 v122, v122
	v_rcp_f32_e32 v123, v123
	s_waitcnt vmcnt(14)
	v_permlane16_swap_b32_e32 v200, v202
	v_permlane16_swap_b32_e32 v201, v203
	v_permlane16_swap_b32_e32 v204, v206
	v_permlane16_swap_b32_e32 v205, v207
	v_lshlrev_b32_e32 v168, 16, v200
	v_and_b32_e32 v169, 0xffff0000, v200
	v_lshlrev_b32_e32 v200, 16, v201
	v_and_b32_e32 v201, 0xffff0000, v201
	v_lshlrev_b32_e32 v170, 16, v202
	v_and_b32_e32 v171, 0xffff0000, v202
	v_lshlrev_b32_e32 v202, 16, v203
	v_and_b32_e32 v203, 0xffff0000, v203
	v_lshlrev_b32_e32 v172, 16, v204
	v_and_b32_e32 v173, 0xffff0000, v204
	v_lshlrev_b32_e32 v204, 16, v205
	v_and_b32_e32 v205, 0xffff0000, v205
	v_lshlrev_b32_e32 v174, 16, v206
	v_and_b32_e32 v175, 0xffff0000, v206
	v_lshlrev_b32_e32 v206, 16, v207
	v_and_b32_e32 v207, 0xffff0000, v207
	v_pk_fma_f32 v[124:125], v[124:125], v[172:173], v[168:169]
	v_pk_fma_f32 v[126:127], v[126:127], v[204:205], v[200:201]
	v_pk_fma_f32 v[120:121], v[120:121], v[174:175], v[170:171]
	v_pk_fma_f32 v[122:123], v[122:123], v[206:207], v[202:203]
	v_mov_b32_e32 v185, v184
	global_store_dwordx4 v185, v[124:127], s[92:93]
	global_store_dwordx4 v185, v[120:123], s[92:93] offset:64
	global_load_dwordx4 v[200:203], v180, s[88:89]
	global_load_dwordx4 v[204:207], v180, s[4:5]
	v_pk_mul_f32 v[116:117], v[116:117], v[186:187]
	v_pk_mul_f32 v[118:119], v[118:119], v[186:187]
	v_pk_mul_f32 v[112:113], v[112:113], v[186:187]
	v_pk_mul_f32 v[114:115], v[114:115], v[186:187]
	v_exp_f32_e32 v116, v116
	v_exp_f32_e32 v117, v117
	v_exp_f32_e32 v118, v118
	v_exp_f32_e32 v119, v119
	v_exp_f32_e32 v112, v112
	v_exp_f32_e32 v113, v113
	v_exp_f32_e32 v114, v114
	v_exp_f32_e32 v115, v115
	v_pk_add_f32 v[116:117], v[116:117], v[188:189]
	v_pk_add_f32 v[118:119], v[118:119], v[188:189]
	v_pk_add_f32 v[112:113], v[112:113], v[188:189]
	v_pk_add_f32 v[114:115], v[114:115], v[188:189]
	v_rcp_f32_e32 v116, v116
	v_rcp_f32_e32 v117, v117
	v_rcp_f32_e32 v118, v118
	v_rcp_f32_e32 v119, v119
	v_rcp_f32_e32 v112, v112
	v_rcp_f32_e32 v113, v113
	v_rcp_f32_e32 v114, v114
	v_rcp_f32_e32 v115, v115
	s_waitcnt vmcnt(16)
	v_permlane16_swap_b32_e32 v208, v210
	v_permlane16_swap_b32_e32 v209, v211
	v_permlane16_swap_b32_e32 v212, v214
	v_permlane16_swap_b32_e32 v213, v215
	v_lshlrev_b32_e32 v168, 16, v208
	v_and_b32_e32 v169, 0xffff0000, v208
	v_lshlrev_b32_e32 v208, 16, v209
	v_and_b32_e32 v209, 0xffff0000, v209
	v_lshlrev_b32_e32 v170, 16, v210
	v_and_b32_e32 v171, 0xffff0000, v210
	v_lshlrev_b32_e32 v210, 16, v211
	v_and_b32_e32 v211, 0xffff0000, v211
	v_lshlrev_b32_e32 v172, 16, v212
	v_and_b32_e32 v173, 0xffff0000, v212
	v_lshlrev_b32_e32 v212, 16, v213
	v_and_b32_e32 v213, 0xffff0000, v213
	v_lshlrev_b32_e32 v174, 16, v214
	v_and_b32_e32 v175, 0xffff0000, v214
	v_lshlrev_b32_e32 v214, 16, v215
	v_and_b32_e32 v215, 0xffff0000, v215
	v_pk_fma_f32 v[116:117], v[116:117], v[172:173], v[168:169]
	v_pk_fma_f32 v[118:119], v[118:119], v[212:213], v[208:209]
	v_pk_fma_f32 v[112:113], v[112:113], v[174:175], v[170:171]
	v_pk_fma_f32 v[114:115], v[114:115], v[214:215], v[210:211]
	global_store_dwordx4 v185, v[116:119], s[92:93] offset:512
	global_store_dwordx4 v185, v[112:115], s[92:93] offset:576
	global_load_dwordx4 v[208:211], v180, s[88:89] offset:256
	global_load_dwordx4 v[212:215], v180, s[4:5] offset:256
	v_pk_mul_f32 v[108:109], v[108:109], v[186:187]
	v_pk_mul_f32 v[110:111], v[110:111], v[186:187]
	v_pk_mul_f32 v[104:105], v[104:105], v[186:187]
	v_pk_mul_f32 v[106:107], v[106:107], v[186:187]
	v_exp_f32_e32 v108, v108
	v_exp_f32_e32 v109, v109
	v_exp_f32_e32 v110, v110
	v_exp_f32_e32 v111, v111
	v_exp_f32_e32 v104, v104
	v_exp_f32_e32 v105, v105
	v_exp_f32_e32 v106, v106
	v_exp_f32_e32 v107, v107
	v_pk_add_f32 v[108:109], v[108:109], v[188:189]
	v_pk_add_f32 v[110:111], v[110:111], v[188:189]
	v_pk_add_f32 v[104:105], v[104:105], v[188:189]
	v_pk_add_f32 v[106:107], v[106:107], v[188:189]
	v_rcp_f32_e32 v108, v108
	v_rcp_f32_e32 v109, v109
	v_rcp_f32_e32 v110, v110
	v_rcp_f32_e32 v111, v111
	v_rcp_f32_e32 v104, v104
	v_rcp_f32_e32 v105, v105
	v_rcp_f32_e32 v106, v106
	v_rcp_f32_e32 v107, v107
	s_waitcnt vmcnt(18)
	v_permlane16_swap_b32_e32 v216, v218
	v_permlane16_swap_b32_e32 v217, v219
	v_permlane16_swap_b32_e32 v220, v222
	v_permlane16_swap_b32_e32 v221, v223
	v_lshlrev_b32_e32 v168, 16, v216
	v_and_b32_e32 v169, 0xffff0000, v216
	v_lshlrev_b32_e32 v216, 16, v217
	v_and_b32_e32 v217, 0xffff0000, v217
	v_lshlrev_b32_e32 v170, 16, v218
	v_and_b32_e32 v171, 0xffff0000, v218
	v_lshlrev_b32_e32 v218, 16, v219
	v_and_b32_e32 v219, 0xffff0000, v219
	v_lshlrev_b32_e32 v172, 16, v220
	v_and_b32_e32 v173, 0xffff0000, v220
	v_lshlrev_b32_e32 v220, 16, v221
	v_and_b32_e32 v221, 0xffff0000, v221
	v_lshlrev_b32_e32 v174, 16, v222
	v_and_b32_e32 v175, 0xffff0000, v222
	v_lshlrev_b32_e32 v222, 16, v223
	v_and_b32_e32 v223, 0xffff0000, v223
	v_pk_fma_f32 v[108:109], v[108:109], v[172:173], v[168:169]
	v_pk_fma_f32 v[110:111], v[110:111], v[220:221], v[216:217]
	v_pk_fma_f32 v[104:105], v[104:105], v[174:175], v[170:171]
	v_pk_fma_f32 v[106:107], v[106:107], v[222:223], v[218:219]
	v_add_u32_e32 v185, 0x10000, v184
	global_store_dwordx4 v185, v[108:111], s[92:93]
	global_store_dwordx4 v185, v[104:107], s[92:93] offset:64
	global_load_dwordx4 v[216:219], v181, s[88:89]
	global_load_dwordx4 v[220:223], v181, s[4:5]
	v_pk_mul_f32 v[100:101], v[100:101], v[186:187]
	v_pk_mul_f32 v[102:103], v[102:103], v[186:187]
	v_pk_mul_f32 v[96:97], v[96:97], v[186:187]
	v_pk_mul_f32 v[98:99], v[98:99], v[186:187]
	v_exp_f32_e32 v100, v100
	v_exp_f32_e32 v101, v101
	v_exp_f32_e32 v102, v102
	v_exp_f32_e32 v103, v103
	v_exp_f32_e32 v96, v96
	v_exp_f32_e32 v97, v97
	v_exp_f32_e32 v98, v98
	v_exp_f32_e32 v99, v99
	v_pk_add_f32 v[100:101], v[100:101], v[188:189]
	v_pk_add_f32 v[102:103], v[102:103], v[188:189]
	v_pk_add_f32 v[96:97], v[96:97], v[188:189]
	v_pk_add_f32 v[98:99], v[98:99], v[188:189]
	v_rcp_f32_e32 v100, v100
	v_rcp_f32_e32 v101, v101
	v_rcp_f32_e32 v102, v102
	v_rcp_f32_e32 v103, v103
	v_rcp_f32_e32 v96, v96
	v_rcp_f32_e32 v97, v97
	v_rcp_f32_e32 v98, v98
	v_rcp_f32_e32 v99, v99
	s_waitcnt vmcnt(20)
	v_permlane16_swap_b32_e32 v224, v226
	v_permlane16_swap_b32_e32 v225, v227
	v_permlane16_swap_b32_e32 v228, v230
	v_permlane16_swap_b32_e32 v229, v231
	v_lshlrev_b32_e32 v168, 16, v224
	v_and_b32_e32 v169, 0xffff0000, v224
	v_lshlrev_b32_e32 v224, 16, v225
	v_and_b32_e32 v225, 0xffff0000, v225
	v_lshlrev_b32_e32 v170, 16, v226
	v_and_b32_e32 v171, 0xffff0000, v226
	v_lshlrev_b32_e32 v226, 16, v227
	v_and_b32_e32 v227, 0xffff0000, v227
	v_lshlrev_b32_e32 v172, 16, v228
	v_and_b32_e32 v173, 0xffff0000, v228
	v_lshlrev_b32_e32 v228, 16, v229
	v_and_b32_e32 v229, 0xffff0000, v229
	v_lshlrev_b32_e32 v174, 16, v230
	v_and_b32_e32 v175, 0xffff0000, v230
	v_lshlrev_b32_e32 v230, 16, v231
	v_and_b32_e32 v231, 0xffff0000, v231
	v_pk_fma_f32 v[100:101], v[100:101], v[172:173], v[168:169]
	v_pk_fma_f32 v[102:103], v[102:103], v[228:229], v[224:225]
	v_pk_fma_f32 v[96:97], v[96:97], v[174:175], v[170:171]
	v_pk_fma_f32 v[98:99], v[98:99], v[230:231], v[226:227]
	global_store_dwordx4 v185, v[100:103], s[92:93] offset:512
	global_store_dwordx4 v185, v[96:99], s[92:93] offset:576
	global_load_dwordx4 v[224:227], v181, s[88:89] offset:256
	global_load_dwordx4 v[228:231], v181, s[4:5] offset:256
	v_pk_mul_f32 v[92:93], v[92:93], v[186:187]
	v_pk_mul_f32 v[94:95], v[94:95], v[186:187]
	v_pk_mul_f32 v[88:89], v[88:89], v[186:187]
	v_pk_mul_f32 v[90:91], v[90:91], v[186:187]
	v_exp_f32_e32 v92, v92
	v_exp_f32_e32 v93, v93
	v_exp_f32_e32 v94, v94
	v_exp_f32_e32 v95, v95
	v_exp_f32_e32 v88, v88
	v_exp_f32_e32 v89, v89
	v_exp_f32_e32 v90, v90
	v_exp_f32_e32 v91, v91
	v_pk_add_f32 v[92:93], v[92:93], v[188:189]
	v_pk_add_f32 v[94:95], v[94:95], v[188:189]
	v_pk_add_f32 v[88:89], v[88:89], v[188:189]
	v_pk_add_f32 v[90:91], v[90:91], v[188:189]
	v_rcp_f32_e32 v92, v92
	v_rcp_f32_e32 v93, v93
	v_rcp_f32_e32 v94, v94
	v_rcp_f32_e32 v95, v95
	v_rcp_f32_e32 v88, v88
	v_rcp_f32_e32 v89, v89
	v_rcp_f32_e32 v90, v90
	v_rcp_f32_e32 v91, v91
	s_waitcnt vmcnt(22)
	v_permlane16_swap_b32_e32 v232, v234
	v_permlane16_swap_b32_e32 v233, v235
	v_permlane16_swap_b32_e32 v236, v238
	v_permlane16_swap_b32_e32 v237, v239
	v_lshlrev_b32_e32 v168, 16, v232
	v_and_b32_e32 v169, 0xffff0000, v232
	v_lshlrev_b32_e32 v232, 16, v233
	v_and_b32_e32 v233, 0xffff0000, v233
	v_lshlrev_b32_e32 v170, 16, v234
	v_and_b32_e32 v171, 0xffff0000, v234
	v_lshlrev_b32_e32 v234, 16, v235
	v_and_b32_e32 v235, 0xffff0000, v235
	v_lshlrev_b32_e32 v172, 16, v236
	v_and_b32_e32 v173, 0xffff0000, v236
	v_lshlrev_b32_e32 v236, 16, v237
	v_and_b32_e32 v237, 0xffff0000, v237
	v_lshlrev_b32_e32 v174, 16, v238
	v_and_b32_e32 v175, 0xffff0000, v238
	v_lshlrev_b32_e32 v238, 16, v239
	v_and_b32_e32 v239, 0xffff0000, v239
	v_pk_fma_f32 v[92:93], v[92:93], v[172:173], v[168:169]
	v_pk_fma_f32 v[94:95], v[94:95], v[236:237], v[232:233]
	v_pk_fma_f32 v[88:89], v[88:89], v[174:175], v[170:171]
	v_pk_fma_f32 v[90:91], v[90:91], v[238:239], v[234:235]
	v_add_u32_e32 v185, 0x20000, v184
	global_store_dwordx4 v185, v[92:95], s[92:93]
	global_store_dwordx4 v185, v[88:91], s[92:93] offset:64
	global_load_dwordx4 v[232:235], v182, s[88:89]
	global_load_dwordx4 v[236:239], v182, s[4:5]
	v_pk_mul_f32 v[84:85], v[84:85], v[186:187]
	v_pk_mul_f32 v[86:87], v[86:87], v[186:187]
	v_pk_mul_f32 v[80:81], v[80:81], v[186:187]
	v_pk_mul_f32 v[82:83], v[82:83], v[186:187]
	v_exp_f32_e32 v84, v84
	v_exp_f32_e32 v85, v85
	v_exp_f32_e32 v86, v86
	v_exp_f32_e32 v87, v87
	v_exp_f32_e32 v80, v80
	v_exp_f32_e32 v81, v81
	v_exp_f32_e32 v82, v82
	v_exp_f32_e32 v83, v83
	v_pk_add_f32 v[84:85], v[84:85], v[188:189]
	v_pk_add_f32 v[86:87], v[86:87], v[188:189]
	v_pk_add_f32 v[80:81], v[80:81], v[188:189]
	v_pk_add_f32 v[82:83], v[82:83], v[188:189]
	v_rcp_f32_e32 v84, v84
	v_rcp_f32_e32 v85, v85
	v_rcp_f32_e32 v86, v86
	v_rcp_f32_e32 v87, v87
	v_rcp_f32_e32 v80, v80
	v_rcp_f32_e32 v81, v81
	v_rcp_f32_e32 v82, v82
	v_rcp_f32_e32 v83, v83
	s_waitcnt vmcnt(24)
	v_permlane16_swap_b32_e32 v240, v242
	v_permlane16_swap_b32_e32 v241, v243
	v_permlane16_swap_b32_e32 v244, v246
	v_permlane16_swap_b32_e32 v245, v247
	v_lshlrev_b32_e32 v168, 16, v240
	v_and_b32_e32 v169, 0xffff0000, v240
	v_lshlrev_b32_e32 v240, 16, v241
	v_and_b32_e32 v241, 0xffff0000, v241
	v_lshlrev_b32_e32 v170, 16, v242
	v_and_b32_e32 v171, 0xffff0000, v242
	v_lshlrev_b32_e32 v242, 16, v243
	v_and_b32_e32 v243, 0xffff0000, v243
	v_lshlrev_b32_e32 v172, 16, v244
	v_and_b32_e32 v173, 0xffff0000, v244
	v_lshlrev_b32_e32 v244, 16, v245
	v_and_b32_e32 v245, 0xffff0000, v245
	v_lshlrev_b32_e32 v174, 16, v246
	v_and_b32_e32 v175, 0xffff0000, v246
	v_lshlrev_b32_e32 v246, 16, v247
	v_and_b32_e32 v247, 0xffff0000, v247
	v_pk_fma_f32 v[84:85], v[84:85], v[172:173], v[168:169]
	v_pk_fma_f32 v[86:87], v[86:87], v[244:245], v[240:241]
	v_pk_fma_f32 v[80:81], v[80:81], v[174:175], v[170:171]
	v_pk_fma_f32 v[82:83], v[82:83], v[246:247], v[242:243]
	global_store_dwordx4 v185, v[84:87], s[92:93] offset:512
	global_store_dwordx4 v185, v[80:83], s[92:93] offset:576
	global_load_dwordx4 v[240:243], v182, s[88:89] offset:256
	global_load_dwordx4 v[244:247], v182, s[4:5] offset:256
	v_pk_mul_f32 v[76:77], v[76:77], v[186:187]
	v_pk_mul_f32 v[78:79], v[78:79], v[186:187]
	v_pk_mul_f32 v[72:73], v[72:73], v[186:187]
	v_pk_mul_f32 v[74:75], v[74:75], v[186:187]
	v_exp_f32_e32 v76, v76
	v_exp_f32_e32 v77, v77
	v_exp_f32_e32 v78, v78
	v_exp_f32_e32 v79, v79
	v_exp_f32_e32 v72, v72
	v_exp_f32_e32 v73, v73
	v_exp_f32_e32 v74, v74
	v_exp_f32_e32 v75, v75
	v_pk_add_f32 v[76:77], v[76:77], v[188:189]
	v_pk_add_f32 v[78:79], v[78:79], v[188:189]
	v_pk_add_f32 v[72:73], v[72:73], v[188:189]
	v_pk_add_f32 v[74:75], v[74:75], v[188:189]
	v_rcp_f32_e32 v76, v76
	v_rcp_f32_e32 v77, v77
	v_rcp_f32_e32 v78, v78
	v_rcp_f32_e32 v79, v79
	v_rcp_f32_e32 v72, v72
	v_rcp_f32_e32 v73, v73
	v_rcp_f32_e32 v74, v74
	v_rcp_f32_e32 v75, v75
	s_waitcnt vmcnt(26)
	v_permlane16_swap_b32_e32 v152, v154
	v_permlane16_swap_b32_e32 v153, v155
	v_permlane16_swap_b32_e32 v156, v158
	v_permlane16_swap_b32_e32 v157, v159
	v_lshlrev_b32_e32 v168, 16, v152
	v_and_b32_e32 v169, 0xffff0000, v152
	v_lshlrev_b32_e32 v152, 16, v153
	v_and_b32_e32 v153, 0xffff0000, v153
	v_lshlrev_b32_e32 v170, 16, v154
	v_and_b32_e32 v171, 0xffff0000, v154
	v_lshlrev_b32_e32 v154, 16, v155
	v_and_b32_e32 v155, 0xffff0000, v155
	v_lshlrev_b32_e32 v172, 16, v156
	v_and_b32_e32 v173, 0xffff0000, v156
	v_lshlrev_b32_e32 v156, 16, v157
	v_and_b32_e32 v157, 0xffff0000, v157
	v_lshlrev_b32_e32 v174, 16, v158
	v_and_b32_e32 v175, 0xffff0000, v158
	v_lshlrev_b32_e32 v158, 16, v159
	v_and_b32_e32 v159, 0xffff0000, v159
	v_pk_fma_f32 v[76:77], v[76:77], v[172:173], v[168:169]
	v_pk_fma_f32 v[78:79], v[78:79], v[156:157], v[152:153]
	v_pk_fma_f32 v[72:73], v[72:73], v[174:175], v[170:171]
	v_pk_fma_f32 v[74:75], v[74:75], v[158:159], v[154:155]
	v_add_u32_e32 v185, 0x30000, v184
	global_store_dwordx4 v185, v[76:79], s[92:93]
	global_store_dwordx4 v185, v[72:75], s[92:93] offset:64
	global_load_dwordx4 v[152:155], v183, s[88:89]
	global_load_dwordx4 v[156:159], v183, s[4:5]
	v_pk_mul_f32 v[68:69], v[68:69], v[186:187]
	v_pk_mul_f32 v[70:71], v[70:71], v[186:187]
	v_pk_mul_f32 v[64:65], v[64:65], v[186:187]
	v_pk_mul_f32 v[66:67], v[66:67], v[186:187]
	v_exp_f32_e32 v68, v68
	v_exp_f32_e32 v69, v69
	v_exp_f32_e32 v70, v70
	v_exp_f32_e32 v71, v71
	v_exp_f32_e32 v64, v64
	v_exp_f32_e32 v65, v65
	v_exp_f32_e32 v66, v66
	v_exp_f32_e32 v67, v67
	v_pk_add_f32 v[68:69], v[68:69], v[188:189]
	v_pk_add_f32 v[70:71], v[70:71], v[188:189]
	v_pk_add_f32 v[64:65], v[64:65], v[188:189]
	v_pk_add_f32 v[66:67], v[66:67], v[188:189]
	v_rcp_f32_e32 v68, v68
	v_rcp_f32_e32 v69, v69
	v_rcp_f32_e32 v70, v70
	v_rcp_f32_e32 v71, v71
	v_rcp_f32_e32 v64, v64
	v_rcp_f32_e32 v65, v65
	v_rcp_f32_e32 v66, v66
	v_rcp_f32_e32 v67, v67
	s_waitcnt vmcnt(28)
	v_permlane16_swap_b32_e32 v160, v162
	v_permlane16_swap_b32_e32 v161, v163
	v_permlane16_swap_b32_e32 v164, v166
	v_permlane16_swap_b32_e32 v165, v167
	v_lshlrev_b32_e32 v168, 16, v160
	v_and_b32_e32 v169, 0xffff0000, v160
	v_lshlrev_b32_e32 v160, 16, v161
	v_and_b32_e32 v161, 0xffff0000, v161
	v_lshlrev_b32_e32 v170, 16, v162
	v_and_b32_e32 v171, 0xffff0000, v162
	v_lshlrev_b32_e32 v162, 16, v163
	v_and_b32_e32 v163, 0xffff0000, v163
	v_lshlrev_b32_e32 v172, 16, v164
	v_and_b32_e32 v173, 0xffff0000, v164
	v_lshlrev_b32_e32 v164, 16, v165
	v_and_b32_e32 v165, 0xffff0000, v165
	v_lshlrev_b32_e32 v174, 16, v166
	v_and_b32_e32 v175, 0xffff0000, v166
	v_lshlrev_b32_e32 v166, 16, v167
	v_and_b32_e32 v167, 0xffff0000, v167
	v_pk_fma_f32 v[68:69], v[68:69], v[172:173], v[168:169]
	v_pk_fma_f32 v[70:71], v[70:71], v[164:165], v[160:161]
	v_pk_fma_f32 v[64:65], v[64:65], v[174:175], v[170:171]
	v_pk_fma_f32 v[66:67], v[66:67], v[166:167], v[162:163]
	global_store_dwordx4 v185, v[68:71], s[92:93] offset:512
	global_store_dwordx4 v185, v[64:67], s[92:93] offset:576
	global_load_dwordx4 v[160:163], v183, s[88:89] offset:256
	global_load_dwordx4 v[164:167], v183, s[4:5] offset:256
	s_mov_b32 s33, s16
	s_mov_b32 s24, s18
	s_mov_b64 s[28:29], s[22:23]
	s_mov_b64 s[26:27], s[20:21]
	v_pk_mul_f32 v[60:61], v[60:61], v[186:187]
	v_pk_mul_f32 v[62:63], v[62:63], v[186:187]
	v_pk_mul_f32 v[56:57], v[56:57], v[186:187]
	v_pk_mul_f32 v[58:59], v[58:59], v[186:187]
	v_exp_f32_e32 v60, v60
	v_exp_f32_e32 v61, v61
	v_exp_f32_e32 v62, v62
	v_exp_f32_e32 v63, v63
	v_exp_f32_e32 v56, v56
	v_exp_f32_e32 v57, v57
	v_exp_f32_e32 v58, v58
	v_exp_f32_e32 v59, v59
	v_pk_add_f32 v[60:61], v[60:61], v[188:189]
	v_pk_add_f32 v[62:63], v[62:63], v[188:189]
	v_pk_add_f32 v[56:57], v[56:57], v[188:189]
	v_pk_add_f32 v[58:59], v[58:59], v[188:189]
	v_rcp_f32_e32 v60, v60
	v_rcp_f32_e32 v61, v61
	v_rcp_f32_e32 v62, v62
	v_rcp_f32_e32 v63, v63
	v_rcp_f32_e32 v56, v56
	v_rcp_f32_e32 v57, v57
	v_rcp_f32_e32 v58, v58
	v_rcp_f32_e32 v59, v59
	s_waitcnt vmcnt(28)
	v_permlane16_swap_b32_e32 v200, v202
	v_permlane16_swap_b32_e32 v201, v203
	v_permlane16_swap_b32_e32 v204, v206
	v_permlane16_swap_b32_e32 v205, v207
	v_lshlrev_b32_e32 v168, 16, v200
	v_and_b32_e32 v169, 0xffff0000, v200
	v_lshlrev_b32_e32 v200, 16, v201
	v_and_b32_e32 v201, 0xffff0000, v201
	v_lshlrev_b32_e32 v170, 16, v202
	v_and_b32_e32 v171, 0xffff0000, v202
	v_lshlrev_b32_e32 v202, 16, v203
	v_and_b32_e32 v203, 0xffff0000, v203
	v_lshlrev_b32_e32 v172, 16, v204
	v_and_b32_e32 v173, 0xffff0000, v204
	v_lshlrev_b32_e32 v204, 16, v205
	v_and_b32_e32 v205, 0xffff0000, v205
	v_lshlrev_b32_e32 v174, 16, v206
	v_and_b32_e32 v175, 0xffff0000, v206
	v_lshlrev_b32_e32 v206, 16, v207
	v_and_b32_e32 v207, 0xffff0000, v207
	v_pk_fma_f32 v[60:61], v[60:61], v[172:173], v[168:169]
	v_pk_fma_f32 v[62:63], v[62:63], v[204:205], v[200:201]
	v_pk_fma_f32 v[56:57], v[56:57], v[174:175], v[170:171]
	v_pk_fma_f32 v[58:59], v[58:59], v[206:207], v[202:203]
	v_add_u32_e32 v185, 0x80000, v184
	global_store_dwordx4 v185, v[60:63], s[92:93]
	global_store_dwordx4 v185, v[56:59], s[92:93] offset:64
	v_pk_mul_f32 v[52:53], v[52:53], v[186:187]
	v_pk_mul_f32 v[54:55], v[54:55], v[186:187]
	v_pk_mul_f32 v[48:49], v[48:49], v[186:187]
	v_pk_mul_f32 v[50:51], v[50:51], v[186:187]
	v_exp_f32_e32 v52, v52
	v_exp_f32_e32 v53, v53
	v_exp_f32_e32 v54, v54
	v_exp_f32_e32 v55, v55
	v_exp_f32_e32 v48, v48
	v_exp_f32_e32 v49, v49
	v_exp_f32_e32 v50, v50
	v_exp_f32_e32 v51, v51
	v_pk_add_f32 v[52:53], v[52:53], v[188:189]
	v_pk_add_f32 v[54:55], v[54:55], v[188:189]
	v_pk_add_f32 v[48:49], v[48:49], v[188:189]
	v_pk_add_f32 v[50:51], v[50:51], v[188:189]
	v_rcp_f32_e32 v52, v52
	v_rcp_f32_e32 v53, v53
	v_rcp_f32_e32 v54, v54
	v_rcp_f32_e32 v55, v55
	v_rcp_f32_e32 v48, v48
	v_rcp_f32_e32 v49, v49
	v_rcp_f32_e32 v50, v50
	v_rcp_f32_e32 v51, v51
	s_waitcnt vmcnt(26)
	v_permlane16_swap_b32_e32 v208, v210
	v_permlane16_swap_b32_e32 v209, v211
	v_permlane16_swap_b32_e32 v212, v214
	v_permlane16_swap_b32_e32 v213, v215
	v_lshlrev_b32_e32 v168, 16, v208
	v_and_b32_e32 v169, 0xffff0000, v208
	v_lshlrev_b32_e32 v208, 16, v209
	v_and_b32_e32 v209, 0xffff0000, v209
	v_lshlrev_b32_e32 v170, 16, v210
	v_and_b32_e32 v171, 0xffff0000, v210
	v_lshlrev_b32_e32 v210, 16, v211
	v_and_b32_e32 v211, 0xffff0000, v211
	v_lshlrev_b32_e32 v172, 16, v212
	v_and_b32_e32 v173, 0xffff0000, v212
	v_lshlrev_b32_e32 v212, 16, v213
	v_and_b32_e32 v213, 0xffff0000, v213
	v_lshlrev_b32_e32 v174, 16, v214
	v_and_b32_e32 v175, 0xffff0000, v214
	v_lshlrev_b32_e32 v214, 16, v215
	v_and_b32_e32 v215, 0xffff0000, v215
	v_pk_fma_f32 v[52:53], v[52:53], v[172:173], v[168:169]
	v_pk_fma_f32 v[54:55], v[54:55], v[212:213], v[208:209]
	v_pk_fma_f32 v[48:49], v[48:49], v[174:175], v[170:171]
	v_pk_fma_f32 v[50:51], v[50:51], v[214:215], v[210:211]
	global_store_dwordx4 v185, v[52:55], s[92:93] offset:512
	global_store_dwordx4 v185, v[48:51], s[92:93] offset:576
	v_pk_mul_f32 v[44:45], v[44:45], v[186:187]
	v_pk_mul_f32 v[46:47], v[46:47], v[186:187]
	v_pk_mul_f32 v[40:41], v[40:41], v[186:187]
	v_pk_mul_f32 v[42:43], v[42:43], v[186:187]
	v_exp_f32_e32 v44, v44
	v_exp_f32_e32 v45, v45
	v_exp_f32_e32 v46, v46
	v_exp_f32_e32 v47, v47
	v_exp_f32_e32 v40, v40
	v_exp_f32_e32 v41, v41
	v_exp_f32_e32 v42, v42
	v_exp_f32_e32 v43, v43
	v_pk_add_f32 v[44:45], v[44:45], v[188:189]
	v_pk_add_f32 v[46:47], v[46:47], v[188:189]
	v_pk_add_f32 v[40:41], v[40:41], v[188:189]
	v_pk_add_f32 v[42:43], v[42:43], v[188:189]
	v_rcp_f32_e32 v44, v44
	v_rcp_f32_e32 v45, v45
	v_rcp_f32_e32 v46, v46
	v_rcp_f32_e32 v47, v47
	v_rcp_f32_e32 v40, v40
	v_rcp_f32_e32 v41, v41
	v_rcp_f32_e32 v42, v42
	v_rcp_f32_e32 v43, v43
	s_waitcnt vmcnt(24)
	v_permlane16_swap_b32_e32 v216, v218
	v_permlane16_swap_b32_e32 v217, v219
	v_permlane16_swap_b32_e32 v220, v222
	v_permlane16_swap_b32_e32 v221, v223
	v_lshlrev_b32_e32 v168, 16, v216
	v_and_b32_e32 v169, 0xffff0000, v216
	v_lshlrev_b32_e32 v216, 16, v217
	v_and_b32_e32 v217, 0xffff0000, v217
	v_lshlrev_b32_e32 v170, 16, v218
	v_and_b32_e32 v171, 0xffff0000, v218
	v_lshlrev_b32_e32 v218, 16, v219
	v_and_b32_e32 v219, 0xffff0000, v219
	v_lshlrev_b32_e32 v172, 16, v220
	v_and_b32_e32 v173, 0xffff0000, v220
	v_lshlrev_b32_e32 v220, 16, v221
	v_and_b32_e32 v221, 0xffff0000, v221
	v_lshlrev_b32_e32 v174, 16, v222
	v_and_b32_e32 v175, 0xffff0000, v222
	v_lshlrev_b32_e32 v222, 16, v223
	v_and_b32_e32 v223, 0xffff0000, v223
	v_pk_fma_f32 v[44:45], v[44:45], v[172:173], v[168:169]
	v_pk_fma_f32 v[46:47], v[46:47], v[220:221], v[216:217]
	v_pk_fma_f32 v[40:41], v[40:41], v[174:175], v[170:171]
	v_pk_fma_f32 v[42:43], v[42:43], v[222:223], v[218:219]
	v_add_u32_e32 v185, 0x90000, v184
	global_store_dwordx4 v185, v[44:47], s[92:93]
	global_store_dwordx4 v185, v[40:43], s[92:93] offset:64
	v_pk_mul_f32 v[36:37], v[36:37], v[186:187]
	v_pk_mul_f32 v[38:39], v[38:39], v[186:187]
	v_pk_mul_f32 v[32:33], v[32:33], v[186:187]
	v_pk_mul_f32 v[34:35], v[34:35], v[186:187]
	v_exp_f32_e32 v36, v36
	v_exp_f32_e32 v37, v37
	v_exp_f32_e32 v38, v38
	v_exp_f32_e32 v39, v39
	v_exp_f32_e32 v32, v32
	v_exp_f32_e32 v33, v33
	v_exp_f32_e32 v34, v34
	v_exp_f32_e32 v35, v35
	v_pk_add_f32 v[36:37], v[36:37], v[188:189]
	v_pk_add_f32 v[38:39], v[38:39], v[188:189]
	v_pk_add_f32 v[32:33], v[32:33], v[188:189]
	v_pk_add_f32 v[34:35], v[34:35], v[188:189]
	v_rcp_f32_e32 v36, v36
	v_rcp_f32_e32 v37, v37
	v_rcp_f32_e32 v38, v38
	v_rcp_f32_e32 v39, v39
	v_rcp_f32_e32 v32, v32
	v_rcp_f32_e32 v33, v33
	v_rcp_f32_e32 v34, v34
	v_rcp_f32_e32 v35, v35
	s_waitcnt vmcnt(22)
	v_permlane16_swap_b32_e32 v224, v226
	v_permlane16_swap_b32_e32 v225, v227
	v_permlane16_swap_b32_e32 v228, v230
	v_permlane16_swap_b32_e32 v229, v231
	v_lshlrev_b32_e32 v168, 16, v224
	v_and_b32_e32 v169, 0xffff0000, v224
	v_lshlrev_b32_e32 v224, 16, v225
	v_and_b32_e32 v225, 0xffff0000, v225
	v_lshlrev_b32_e32 v170, 16, v226
	v_and_b32_e32 v171, 0xffff0000, v226
	v_lshlrev_b32_e32 v226, 16, v227
	v_and_b32_e32 v227, 0xffff0000, v227
	v_lshlrev_b32_e32 v172, 16, v228
	v_and_b32_e32 v173, 0xffff0000, v228
	v_lshlrev_b32_e32 v228, 16, v229
	v_and_b32_e32 v229, 0xffff0000, v229
	v_lshlrev_b32_e32 v174, 16, v230
	v_and_b32_e32 v175, 0xffff0000, v230
	v_lshlrev_b32_e32 v230, 16, v231
	v_and_b32_e32 v231, 0xffff0000, v231
	v_pk_fma_f32 v[36:37], v[36:37], v[172:173], v[168:169]
	v_pk_fma_f32 v[38:39], v[38:39], v[228:229], v[224:225]
	v_pk_fma_f32 v[32:33], v[32:33], v[174:175], v[170:171]
	v_pk_fma_f32 v[34:35], v[34:35], v[230:231], v[226:227]
	global_store_dwordx4 v185, v[36:39], s[92:93] offset:512
	global_store_dwordx4 v185, v[32:35], s[92:93] offset:576
	v_pk_mul_f32 v[28:29], v[28:29], v[186:187]
	v_pk_mul_f32 v[30:31], v[30:31], v[186:187]
	v_pk_mul_f32 v[24:25], v[24:25], v[186:187]
	v_pk_mul_f32 v[26:27], v[26:27], v[186:187]
	v_exp_f32_e32 v28, v28
	v_exp_f32_e32 v29, v29
	v_exp_f32_e32 v30, v30
	v_exp_f32_e32 v31, v31
	v_exp_f32_e32 v24, v24
	v_exp_f32_e32 v25, v25
	v_exp_f32_e32 v26, v26
	v_exp_f32_e32 v27, v27
	v_pk_add_f32 v[28:29], v[28:29], v[188:189]
	v_pk_add_f32 v[30:31], v[30:31], v[188:189]
	v_pk_add_f32 v[24:25], v[24:25], v[188:189]
	v_pk_add_f32 v[26:27], v[26:27], v[188:189]
	v_rcp_f32_e32 v28, v28
	v_rcp_f32_e32 v29, v29
	v_rcp_f32_e32 v30, v30
	v_rcp_f32_e32 v31, v31
	v_rcp_f32_e32 v24, v24
	v_rcp_f32_e32 v25, v25
	v_rcp_f32_e32 v26, v26
	v_rcp_f32_e32 v27, v27
	s_waitcnt vmcnt(20)
	v_permlane16_swap_b32_e32 v232, v234
	v_permlane16_swap_b32_e32 v233, v235
	v_permlane16_swap_b32_e32 v236, v238
	v_permlane16_swap_b32_e32 v237, v239
	v_lshlrev_b32_e32 v168, 16, v232
	v_and_b32_e32 v169, 0xffff0000, v232
	v_lshlrev_b32_e32 v232, 16, v233
	v_and_b32_e32 v233, 0xffff0000, v233
	v_lshlrev_b32_e32 v170, 16, v234
	v_and_b32_e32 v171, 0xffff0000, v234
	v_lshlrev_b32_e32 v234, 16, v235
	v_and_b32_e32 v235, 0xffff0000, v235
	v_lshlrev_b32_e32 v172, 16, v236
	v_and_b32_e32 v173, 0xffff0000, v236
	v_lshlrev_b32_e32 v236, 16, v237
	v_and_b32_e32 v237, 0xffff0000, v237
	v_lshlrev_b32_e32 v174, 16, v238
	v_and_b32_e32 v175, 0xffff0000, v238
	v_lshlrev_b32_e32 v238, 16, v239
	v_and_b32_e32 v239, 0xffff0000, v239
	v_pk_fma_f32 v[28:29], v[28:29], v[172:173], v[168:169]
	v_pk_fma_f32 v[30:31], v[30:31], v[236:237], v[232:233]
	v_pk_fma_f32 v[24:25], v[24:25], v[174:175], v[170:171]
	v_pk_fma_f32 v[26:27], v[26:27], v[238:239], v[234:235]
	v_add_u32_e32 v185, 0xa0000, v184
	global_store_dwordx4 v185, v[28:31], s[92:93]
	global_store_dwordx4 v185, v[24:27], s[92:93] offset:64
	v_pk_mul_f32 v[20:21], v[20:21], v[186:187]
	v_pk_mul_f32 v[22:23], v[22:23], v[186:187]
	v_pk_mul_f32 v[16:17], v[16:17], v[186:187]
	v_pk_mul_f32 v[18:19], v[18:19], v[186:187]
	v_exp_f32_e32 v20, v20
	v_exp_f32_e32 v21, v21
	v_exp_f32_e32 v22, v22
	v_exp_f32_e32 v23, v23
	v_exp_f32_e32 v16, v16
	v_exp_f32_e32 v17, v17
	v_exp_f32_e32 v18, v18
	v_exp_f32_e32 v19, v19
	v_pk_add_f32 v[20:21], v[20:21], v[188:189]
	v_pk_add_f32 v[22:23], v[22:23], v[188:189]
	v_pk_add_f32 v[16:17], v[16:17], v[188:189]
	v_pk_add_f32 v[18:19], v[18:19], v[188:189]
	v_rcp_f32_e32 v20, v20
	v_rcp_f32_e32 v21, v21
	v_rcp_f32_e32 v22, v22
	v_rcp_f32_e32 v23, v23
	v_rcp_f32_e32 v16, v16
	v_rcp_f32_e32 v17, v17
	v_rcp_f32_e32 v18, v18
	v_rcp_f32_e32 v19, v19
	s_waitcnt vmcnt(18)
	v_permlane16_swap_b32_e32 v240, v242
	v_permlane16_swap_b32_e32 v241, v243
	v_permlane16_swap_b32_e32 v244, v246
	v_permlane16_swap_b32_e32 v245, v247
	v_lshlrev_b32_e32 v168, 16, v240
	v_and_b32_e32 v169, 0xffff0000, v240
	v_lshlrev_b32_e32 v240, 16, v241
	v_and_b32_e32 v241, 0xffff0000, v241
	v_lshlrev_b32_e32 v170, 16, v242
	v_and_b32_e32 v171, 0xffff0000, v242
	v_lshlrev_b32_e32 v242, 16, v243
	v_and_b32_e32 v243, 0xffff0000, v243
	v_lshlrev_b32_e32 v172, 16, v244
	v_and_b32_e32 v173, 0xffff0000, v244
	v_lshlrev_b32_e32 v244, 16, v245
	v_and_b32_e32 v245, 0xffff0000, v245
	v_lshlrev_b32_e32 v174, 16, v246
	v_and_b32_e32 v175, 0xffff0000, v246
	v_lshlrev_b32_e32 v246, 16, v247
	v_and_b32_e32 v247, 0xffff0000, v247
	v_pk_fma_f32 v[20:21], v[20:21], v[172:173], v[168:169]
	v_pk_fma_f32 v[22:23], v[22:23], v[244:245], v[240:241]
	v_pk_fma_f32 v[16:17], v[16:17], v[174:175], v[170:171]
	v_pk_fma_f32 v[18:19], v[18:19], v[246:247], v[242:243]
	global_store_dwordx4 v185, v[20:23], s[92:93] offset:512
	global_store_dwordx4 v185, v[16:19], s[92:93] offset:576
	v_pk_mul_f32 v[12:13], v[12:13], v[186:187]
	v_pk_mul_f32 v[14:15], v[14:15], v[186:187]
	v_pk_mul_f32 v[8:9], v[8:9], v[186:187]
	v_pk_mul_f32 v[10:11], v[10:11], v[186:187]
	v_exp_f32_e32 v12, v12
	v_exp_f32_e32 v13, v13
	v_exp_f32_e32 v14, v14
	v_exp_f32_e32 v15, v15
	v_exp_f32_e32 v8, v8
	v_exp_f32_e32 v9, v9
	v_exp_f32_e32 v10, v10
	v_exp_f32_e32 v11, v11
	v_pk_add_f32 v[12:13], v[12:13], v[188:189]
	v_pk_add_f32 v[14:15], v[14:15], v[188:189]
	v_pk_add_f32 v[8:9], v[8:9], v[188:189]
	v_pk_add_f32 v[10:11], v[10:11], v[188:189]
	v_rcp_f32_e32 v12, v12
	v_rcp_f32_e32 v13, v13
	v_rcp_f32_e32 v14, v14
	v_rcp_f32_e32 v15, v15
	v_rcp_f32_e32 v8, v8
	v_rcp_f32_e32 v9, v9
	v_rcp_f32_e32 v10, v10
	v_rcp_f32_e32 v11, v11
	s_waitcnt vmcnt(16)
	v_permlane16_swap_b32_e32 v152, v154
	v_permlane16_swap_b32_e32 v153, v155
	v_permlane16_swap_b32_e32 v156, v158
	v_permlane16_swap_b32_e32 v157, v159
	v_lshlrev_b32_e32 v168, 16, v152
	v_and_b32_e32 v169, 0xffff0000, v152
	v_lshlrev_b32_e32 v152, 16, v153
	v_and_b32_e32 v153, 0xffff0000, v153
	v_lshlrev_b32_e32 v170, 16, v154
	v_and_b32_e32 v171, 0xffff0000, v154
	v_lshlrev_b32_e32 v154, 16, v155
	v_and_b32_e32 v155, 0xffff0000, v155
	v_lshlrev_b32_e32 v172, 16, v156
	v_and_b32_e32 v173, 0xffff0000, v156
	v_lshlrev_b32_e32 v156, 16, v157
	v_and_b32_e32 v157, 0xffff0000, v157
	v_lshlrev_b32_e32 v174, 16, v158
	v_and_b32_e32 v175, 0xffff0000, v158
	v_lshlrev_b32_e32 v158, 16, v159
	v_and_b32_e32 v159, 0xffff0000, v159
	v_pk_fma_f32 v[12:13], v[12:13], v[172:173], v[168:169]
	v_pk_fma_f32 v[14:15], v[14:15], v[156:157], v[152:153]
	v_pk_fma_f32 v[8:9], v[8:9], v[174:175], v[170:171]
	v_pk_fma_f32 v[10:11], v[10:11], v[158:159], v[154:155]
	v_add_u32_e32 v185, 0xb0000, v184
	global_store_dwordx4 v185, v[12:15], s[92:93]
	global_store_dwordx4 v185, v[8:11], s[92:93] offset:64
	v_pk_mul_f32 v[4:5], v[4:5], v[186:187]
	v_pk_mul_f32 v[6:7], v[6:7], v[186:187]
	v_pk_mul_f32 v[0:1], v[0:1], v[186:187]
	v_pk_mul_f32 v[2:3], v[2:3], v[186:187]
	v_exp_f32_e32 v4, v4
	v_exp_f32_e32 v5, v5
	v_exp_f32_e32 v6, v6
	v_exp_f32_e32 v7, v7
	v_exp_f32_e32 v0, v0
	v_exp_f32_e32 v1, v1
	v_exp_f32_e32 v2, v2
	v_exp_f32_e32 v3, v3
	v_pk_add_f32 v[4:5], v[4:5], v[188:189]
	v_pk_add_f32 v[6:7], v[6:7], v[188:189]
	v_pk_add_f32 v[0:1], v[0:1], v[188:189]
	v_pk_add_f32 v[2:3], v[2:3], v[188:189]
	v_rcp_f32_e32 v4, v4
	v_rcp_f32_e32 v5, v5
	v_rcp_f32_e32 v6, v6
	v_rcp_f32_e32 v7, v7
	v_rcp_f32_e32 v0, v0
	v_rcp_f32_e32 v1, v1
	v_rcp_f32_e32 v2, v2
	v_rcp_f32_e32 v3, v3
	s_waitcnt vmcnt(14)
	v_permlane16_swap_b32_e32 v160, v162
	v_permlane16_swap_b32_e32 v161, v163
	v_permlane16_swap_b32_e32 v164, v166
	v_permlane16_swap_b32_e32 v165, v167
	v_lshlrev_b32_e32 v168, 16, v160
	v_and_b32_e32 v169, 0xffff0000, v160
	v_lshlrev_b32_e32 v160, 16, v161
	v_and_b32_e32 v161, 0xffff0000, v161
	v_lshlrev_b32_e32 v170, 16, v162
	v_and_b32_e32 v171, 0xffff0000, v162
	v_lshlrev_b32_e32 v162, 16, v163
	v_and_b32_e32 v163, 0xffff0000, v163
	v_lshlrev_b32_e32 v172, 16, v164
	v_and_b32_e32 v173, 0xffff0000, v164
	v_lshlrev_b32_e32 v164, 16, v165
	v_and_b32_e32 v165, 0xffff0000, v165
	v_lshlrev_b32_e32 v174, 16, v166
	v_and_b32_e32 v175, 0xffff0000, v166
	v_lshlrev_b32_e32 v166, 16, v167
	v_and_b32_e32 v167, 0xffff0000, v167
	v_pk_fma_f32 v[4:5], v[4:5], v[172:173], v[168:169]
	v_pk_fma_f32 v[6:7], v[6:7], v[164:165], v[160:161]
	v_pk_fma_f32 v[0:1], v[0:1], v[174:175], v[170:171]
	v_pk_fma_f32 v[2:3], v[2:3], v[166:167], v[162:163]
	global_store_dwordx4 v185, v[4:7], s[92:93] offset:512
	global_store_dwordx4 v185, v[0:3], s[92:93] offset:576
	s_cbranch_vccz .LBB0_1607
	s_waitcnt vmcnt(0)
	s_cmpk_gt_u32 s34, 0xff
	s_cbranch_scc1 .LBB0_1618
	s_barrier
